# nt policy extended to P0 weight-transpose loads, P4a/P4b RAW reads, P6 per-token loads, gate epilogue x1/pl loads
# speedup vs baseline: 1.0487x; 1.0114x over previous
; __device__ __forceinline__ unsigned pk2(float a, float b) { f32x2_t v = {a, b}; bf16x2v_t r = __builtin_convertvector(v, bf16x2v_t); return __builtin_bit_cast(unsigned, r); }
; #define LAS __attribute__((address_space(3)))
; template <bool WINMAP = false>
; __device__ __forceinline__ void p0_transpose_item(const float* W, int N, bf16_t* WT, int ldt, int row_off, int col_off, LAS float* scr, int item, int lane, const float* gk = nullptr) {
;     const int nblk = N / 32, kb = item / nblk, nb = item % nblk, k0 = 64 * kb, n0 = 32 * nb;
;     { f32x4 v[8];
; #pragma unroll
;       for (int i = 0; i < 8; ++i) v[i] = *(const f32x4*)(W + (size_t)(k0 + 8 * i + (lane >> 3)) * N + n0 + 4 * (lane & 7));
; #pragma unroll
;       for (int i = 0; i < 8; ++i) { const int kk = 8 * i + (lane >> 3); const float gg = gk ? gk[k0 + kk] : 1.f; LAS float* d = scr + kk * 33 + 4 * (lane & 7);
;           d[0] = v[i][0] * gg; d[1] = v[i][1] * gg; d[2] = v[i][2] * gg; d[3] = v[i][3] * gg; } }
;     asm volatile("s_waitcnt lgkmcnt(0)" ::: "memory");
;     const int c = lane & 7;
; #pragma unroll
;     for (int j = 0; j < 4; ++j) { const int n = (lane >> 3) + 8 * j; const LAS float* s = scr + (8 * c) * 33 + n;
;         u32x4 o; o.x = pk2(s[0 * 33], s[1 * 33]); o.y = pk2(s[2 * 33], s[3 * 33]); o.z = pk2(s[4 * 33], s[5 * 33]); o.w = pk2(s[6 * 33], s[7 * 33]);
;         *(u32x4*)(WT + (size_t)(WINMAP ? win_row(n0 + n) : row_off + n0 + n) * ldt + col_off + k0 + 8 * c) = o; }
;     asm volatile("s_waitcnt lgkmcnt(0)" ::: "memory");
; __device__ __forceinline__ void phase0(const Args& a, LAS unsigned char* lds, int gw_, int NGW, int wave, int lane_) {
;     ...
;         if (r < I_UKV) { p0_transpose_item(a.w_ukv, 1024, WupT, UPK, 768, 256, scr, r, lane, a.g_ckv); continue; } r -= I_UKV;
;         p0_transpose_item(a.w_pl, DM, WplT, PLE, 0, 0, scr, r, lane);
.LBB0_22:
	s_cmpk_gt_i32 s30, 0x5df
	s_mov_b64 s[0:1], -1
	s_cbranch_scc0 .LBB0_48
	s_cmpk_gt_u32 s30, 0x63f
	s_cbranch_scc0 .LBB0_37
	s_cmpk_gt_u32 s30, 0x67f
	s_cbranch_scc0 .LBB0_26
	s_and_b32 s0, s18, 0x1c0
	s_xor_b32 s0, s0, 0x100
	s_and_b32 s1, s3, 0x3e0
	v_add_u32_e32 v0, s0, v53
	s_lshl_b32 s4, s1, 2
	v_ashrrev_i32_e32 v1, 31, v0
	v_lshl_add_u64 v[2:3], v[40:41], 0, s[4:5]
	v_lshlrev_b64 v[0:1], 12, v[0:1]
	v_lshl_add_u64 v[28:29], v[2:3], 0, v[0:1]
	v_add_co_u32_e32 v4, vcc, 0x8000, v28
	v_add_u32_e32 v80, s1, v55
	s_nop 0
	v_addc_co_u32_e32 v5, vcc, 0, v29, vcc
	v_add_co_u32_e32 v8, vcc, 0x10000, v28
	global_load_dwordx4 v[0:3], v[28:29], off nt
	s_nop 0
	global_load_dwordx4 v[4:7], v[4:5], off nt
	v_addc_co_u32_e32 v9, vcc, 0, v29, vcc
	v_add_co_u32_e32 v12, vcc, 0x18000, v28
	s_lshl_b32 s4, s0, 1
	s_nop 0
	v_addc_co_u32_e32 v13, vcc, 0, v29, vcc
	v_add_co_u32_e32 v16, vcc, 0x20000, v28
	global_load_dwordx4 v[8:11], v[8:9], off nt
	s_nop 0
	global_load_dwordx4 v[12:15], v[12:13], off nt
	v_addc_co_u32_e32 v17, vcc, 0, v29, vcc
	v_add_co_u32_e32 v20, vcc, 0x28000, v28
	v_ashrrev_i32_e32 v81, 31, v80
	s_nop 0
	v_addc_co_u32_e32 v21, vcc, 0, v29, vcc
	global_load_dwordx4 v[16:19], v[16:17], off nt
	s_nop 0
	global_load_dwordx4 v[20:23], v[20:21], off nt
	v_add_co_u32_e32 v24, vcc, 0x30000, v28
	v_lshl_add_u64 v[82:83], v[34:35], 0, s[4:5]
	s_nop 0
	v_addc_co_u32_e32 v25, vcc, 0, v29, vcc
	global_load_dwordx4 v[24:27], v[24:25], off nt
	v_add_co_u32_e32 v28, vcc, 0x38000, v28
	v_lshlrev_b64 v[80:81], 9, v[80:81]
	s_nop 0
	v_addc_co_u32_e32 v29, vcc, 0, v29, vcc
	global_load_dwordx4 v[28:31], v[28:29], off nt
	v_add_u32_e32 v48, s1, v53
	v_lshl_add_u64 v[80:81], v[82:83], 0, v[80:81]
	v_ashrrev_i32_e32 v49, 31, v48
	v_lshlrev_b64 v[48:49], 9, v[48:49]
	v_lshl_add_u64 v[48:49], v[82:83], 0, v[48:49]
	s_waitcnt vmcnt(7)
	ds_write2_b32 v65, v0, v1 offset1:1
	ds_write2_b32 v65, v2, v3 offset0:2 offset1:3
	s_waitcnt vmcnt(6)
	ds_write2_b32 v66, v4, v5 offset1:1
	ds_write2_b32 v67, v6, v7 offset1:1
	s_waitcnt vmcnt(5)
	ds_write2_b32 v68, v8, v9 offset1:1
	ds_write2_b32 v69, v10, v11 offset1:1
	s_waitcnt vmcnt(4)
	ds_write2_b32 v70, v12, v13 offset1:1
	ds_write2_b32 v71, v14, v15 offset1:1
	s_waitcnt vmcnt(3)
	ds_write2_b32 v72, v16, v17 offset1:1
	ds_write2_b32 v73, v18, v19 offset1:1
	s_waitcnt vmcnt(2)
	ds_write2_b32 v74, v20, v21 offset1:1
	ds_write2_b32 v75, v22, v23 offset1:1
	s_waitcnt vmcnt(1)
	ds_write2_b32 v76, v24, v25 offset1:1
	ds_write2_b32 v77, v26, v27 offset1:1
	s_waitcnt vmcnt(0)
	ds_write2_b32 v78, v28, v29 offset1:1
	ds_write2_b32 v79, v30, v31 offset1:1
	s_waitcnt lgkmcnt(0)
	ds_read2_b32 v[4:5], v58 offset0:33 offset1:41
	ds_read2_b32 v[6:7], v58 offset1:8
	ds_read2_b32 v[8:9], v58 offset0:66 offset1:74
	ds_read2_b32 v[10:11], v58 offset0:99 offset1:107
	ds_read2_b32 v[12:13], v58 offset0:132 offset1:140
	ds_read2_b32 v[14:15], v58 offset0:165 offset1:173
	ds_read2_b32 v[16:17], v58 offset0:198 offset1:206
	ds_read2_b32 v[18:19], v58 offset0:231 offset1:239
	ds_read2_b32 v[20:21], v58 offset0:49 offset1:57
	ds_read2_b32 v[22:23], v58 offset0:16 offset1:24
	ds_read2_b32 v[24:25], v58 offset0:82 offset1:90
	ds_read2_b32 v[26:27], v58 offset0:115 offset1:123
	ds_read2_b32 v[28:29], v58 offset0:148 offset1:156
	ds_read2_b32 v[30:31], v58 offset0:181 offset1:189
	ds_read2_b32 v[84:85], v58 offset0:214 offset1:222
	s_waitcnt lgkmcnt(13)
	v_cvt_pk_bf16_f32 v0, v6, v4
	s_waitcnt lgkmcnt(11)
	v_cvt_pk_bf16_f32 v1, v8, v10
	v_cvt_pk_bf16_f32 v4, v7, v5
	v_cvt_pk_bf16_f32 v5, v9, v11
	ds_read2_b32 v[8:9], v58 offset0:247 offset1:255
	s_waitcnt lgkmcnt(10)
	v_cvt_pk_bf16_f32 v6, v13, v15
	s_waitcnt lgkmcnt(8)
	v_cvt_pk_bf16_f32 v7, v17, v19
	global_store_dwordx4 v[80:81], v[4:7], off
	v_cvt_pk_bf16_f32 v2, v12, v14
	v_cvt_pk_bf16_f32 v3, v16, v18
	v_add_u32_e32 v4, s1, v56
	v_ashrrev_i32_e32 v5, 31, v4
	v_lshlrev_b64 v[4:5], 9, v[4:5]
	global_store_dwordx4 v[48:49], v[0:3], off
	v_lshl_add_u64 v[4:5], v[82:83], 0, v[4:5]
	s_waitcnt lgkmcnt(6)
	v_cvt_pk_bf16_f32 v0, v22, v20
	s_waitcnt lgkmcnt(4)
	v_cvt_pk_bf16_f32 v1, v24, v26
	s_waitcnt lgkmcnt(2)
	v_cvt_pk_bf16_f32 v2, v28, v30
	s_waitcnt lgkmcnt(0)
	v_cvt_pk_bf16_f32 v3, v84, v8
	global_store_dwordx4 v[4:5], v[0:3], off
	v_add_u32_e32 v4, s1, v57
	v_ashrrev_i32_e32 v5, 31, v4
	v_lshlrev_b64 v[4:5], 9, v[4:5]
	v_cvt_pk_bf16_f32 v0, v23, v21
	v_cvt_pk_bf16_f32 v1, v25, v27
	v_cvt_pk_bf16_f32 v2, v29, v31
	v_cvt_pk_bf16_f32 v3, v85, v9
	v_lshl_add_u64 v[4:5], v[82:83], 0, v[4:5]
	global_store_dwordx4 v[4:5], v[0:3], off
	s_waitcnt lgkmcnt(0)
	s_mov_b64 s[0:1], 0
.LBB0_26:
	s_andn2_b64 vcc, exec, s[0:1]
	s_cbranch_vccnz .LBB0_36
	s_add_i32 s0, s30, 0xfffff9c0
	s_add_i32 s1, s30, 0xfffff9a0
	s_cmp_lt_u32 s0, 32
	s_cselect_b32 s1, s0, s1
	s_cmp_gt_u32 s0, 31
	s_cselect_b32 s4, 64, 0
	s_lshl_b32 s14, s1, 5
	v_add_u32_e32 v48, s4, v53
	s_ashr_i32 s15, s14, 31
	v_ashrrev_i32_e32 v49, 31, v48
	v_lshl_add_u64 v[0:1], s[14:15], 2, v[42:43]
	v_lshlrev_b64 v[2:3], 12, v[48:49]
	v_lshl_add_u64 v[0:1], v[0:1], 0, v[2:3]
	v_add_co_u32_e32 v2, vcc, s20, v0
	v_readlane_b32 s36, v255, 0
	s_nop 0
	v_addc_co_u32_e32 v3, vcc, 0, v1, vcc
	global_load_dwordx4 v[28:31], v[0:1], off nt
	global_load_dwordx4 v[24:27], v[2:3], off nt
	v_add_co_u32_e32 v2, vcc, s21, v0
	v_cndmask_b32_e64 v52, 0, 1, s[10:11]
	s_nop 0
	v_addc_co_u32_e32 v3, vcc, 0, v1, vcc
	v_add_co_u32_e32 v4, vcc, s22, v0
	v_readlane_b32 s50, v255, 14
	s_nop 0
	v_addc_co_u32_e32 v5, vcc, 0, v1, vcc
	global_load_dwordx4 v[20:23], v[2:3], off nt
	global_load_dwordx4 v[16:19], v[4:5], off nt
	v_add_co_u32_e32 v2, vcc, s23, v0
	v_readlane_b32 s51, v255, 15
	s_nop 0
	v_addc_co_u32_e32 v3, vcc, 0, v1, vcc
	v_add_co_u32_e32 v4, vcc, 0x28000, v0
	v_mov_b32_e32 v50, 1.0
	s_nop 0
	v_addc_co_u32_e32 v5, vcc, 0, v1, vcc
	global_load_dwordx4 v[12:15], v[2:3], off nt
	global_load_dwordx4 v[8:11], v[4:5], off nt
	v_add_co_u32_e32 v2, vcc, 0x30000, v0
	v_cmp_ne_u32_e64 s[0:1], 1, v52
	s_nop 0
	v_addc_co_u32_e32 v3, vcc, 0, v1, vcc
	v_add_co_u32_e32 v0, vcc, 0x38000, v0
	v_lshl_add_u64 v[48:49], v[48:49], 2, s[50:51]
	s_nop 0
	v_addc_co_u32_e32 v1, vcc, 0, v1, vcc
	global_load_dwordx4 v[4:7], v[2:3], off nt
	s_nop 0
	global_load_dwordx4 v[0:3], v[0:1], off nt
	s_andn2_b64 vcc, exec, s[10:11]
	v_mov_b32_e32 v52, 1.0
	v_readlane_b32 s37, v255, 1
	v_readlane_b32 s38, v255, 2
	v_readlane_b32 s39, v255, 3
	v_readlane_b32 s40, v255, 4
	v_readlane_b32 s41, v255, 5
	v_readlane_b32 s42, v255, 6
	v_readlane_b32 s43, v255, 7
	v_readlane_b32 s44, v255, 8
	v_readlane_b32 s45, v255, 9
	v_readlane_b32 s46, v255, 10
	v_readlane_b32 s47, v255, 11
	v_readlane_b32 s48, v255, 12
	v_readlane_b32 s49, v255, 13
	s_cbranch_vccnz .LBB0_29
	global_load_dword v80, v[48:49], off
	global_load_dword v52, v[48:49], off offset:32
	s_waitcnt vmcnt(1)
	v_pk_mul_f32 v[28:29], v[28:29], v[80:81] op_sel_hi:[1,0]
	v_pk_mul_f32 v[30:31], v[30:31], v[80:81] op_sel_hi:[1,0]

; #define LAS __attribute__((address_space(3)))
; template <bool WINMAP = false>
; __device__ __forceinline__ void p0_transpose_item(const float* W, int N, bf16_t* WT, int ldt, int row_off, int col_off, LAS float* scr, int item, int lane, const float* gk = nullptr) {
;     const int nblk = N / 32, kb = item / nblk, nb = item % nblk, k0 = 64 * kb, n0 = 32 * nb;
;     { f32x4 v[8];
; #pragma unroll
;       for (int i = 0; i < 8; ++i) v[i] = *(const f32x4*)(W + (size_t)(k0 + 8 * i + (lane >> 3)) * N + n0 + 4 * (lane & 7));
; #pragma unroll
;       for (int i = 0; i < 8; ++i) { const int kk = 8 * i + (lane >> 3); const float gg = gk ? gk[k0 + kk] : 1.f; LAS float* d = scr + kk * 33 + 4 * (lane & 7);
;           d[0] = v[i][0] * gg; d[1] = v[i][1] * gg; d[2] = v[i][2] * gg; d[3] = v[i][3] * gg; } }
;     asm volatile("s_waitcnt lgkmcnt(0)" ::: "memory");
; __device__ __forceinline__ void phase0(const Args& a, LAS unsigned char* lds, int gw_, int NGW, int wave, int lane_) {
;     ...
;         if (r < I_UQ) { p0_transpose_item(a.w_uq, 768, WupT, UPK, 0, 0, scr, r, lane, a.g_cq); continue; } r -= I_UQ;
.LBB0_37:
	s_andn2_b64 vcc, exec, s[0:1]
	s_cbranch_vccnz .LBB0_47
	s_add_i32 s0, s30, 32
	s_and_b32 s1, s0, 0xff
	s_mulk_i32 s1, 0xab
	s_bfe_u32 s1, s1, 0x4000c
	s_mul_i32 s4, s1, 24
	s_sub_i32 s0, s0, s4
	s_and_b32 s15, s0, 0xff
	s_lshl_b32 s14, s1, 6
	v_add_u32_e32 v48, s14, v53
	s_lshl_b32 s4, s15, 7
	v_lshl_add_u64 v[0:1], v[44:45], 0, s[4:5]
	v_add_u32_e32 v4, 8, v48
	v_mad_i64_i32 v[2:3], s[0:1], v48, s25, v[0:1]
	v_mad_i64_i32 v[4:5], s[0:1], v4, s25, v[0:1]
	global_load_dwordx4 v[28:31], v[2:3], off nt
	global_load_dwordx4 v[24:27], v[4:5], off nt
	v_add_u32_e32 v2, 16, v48
	v_add_u32_e32 v4, 24, v48
	v_mad_i64_i32 v[2:3], s[0:1], v2, s25, v[0:1]
	v_mad_i64_i32 v[4:5], s[0:1], v4, s25, v[0:1]
	global_load_dwordx4 v[20:23], v[2:3], off nt
	global_load_dwordx4 v[16:19], v[4:5], off nt
	v_add_u32_e32 v2, 32, v48
	v_add_u32_e32 v4, 40, v48
	v_mad_i64_i32 v[2:3], s[0:1], v2, s25, v[0:1]
	v_mad_i64_i32 v[4:5], s[0:1], v4, s25, v[0:1]
	global_load_dwordx4 v[12:15], v[2:3], off nt
	global_load_dwordx4 v[8:11], v[4:5], off nt
	v_add_u32_e32 v2, 48, v48
	v_add_u32_e32 v4, 56, v48
	v_mad_i64_i32 v[2:3], s[0:1], v2, s25, v[0:1]
	v_mad_i64_i32 v[0:1], s[0:1], v4, s25, v[0:1]
	global_load_dwordx4 v[4:7], v[2:3], off nt
	s_nop 0
	global_load_dwordx4 v[0:3], v[0:1], off nt
	v_readlane_b32 s36, v255, 0
	v_ashrrev_i32_e32 v49, 31, v48
	v_cndmask_b32_e64 v52, 0, 1, s[12:13]
	v_readlane_b32 s46, v255, 10
	v_readlane_b32 s47, v255, 11
	v_mov_b32_e32 v50, 1.0
	v_cmp_ne_u32_e64 s[0:1], 1, v52
	s_andn2_b64 vcc, exec, s[12:13]
	v_lshl_add_u64 v[48:49], v[48:49], 2, s[46:47]
	v_mov_b32_e32 v52, 1.0
	v_readlane_b32 s37, v255, 1
	v_readlane_b32 s38, v255, 2
	v_readlane_b32 s39, v255, 3
	v_readlane_b32 s40, v255, 4
	v_readlane_b32 s41, v255, 5
	v_readlane_b32 s42, v255, 6
	v_readlane_b32 s43, v255, 7
	v_readlane_b32 s44, v255, 8
	v_readlane_b32 s45, v255, 9
	v_readlane_b32 s48, v255, 12
	v_readlane_b32 s49, v255, 13
	v_readlane_b32 s50, v255, 14
	v_readlane_b32 s51, v255, 15
	s_cbranch_vccnz .LBB0_40
	global_load_dword v80, v[48:49], off
	global_load_dword v52, v[48:49], off offset:32
	s_waitcnt vmcnt(1)
	v_pk_mul_f32 v[28:29], v[28:29], v[80:81] op_sel_hi:[1,0]
	v_pk_mul_f32 v[30:31], v[30:31], v[80:81] op_sel_hi:[1,0]

; __device__ __forceinline__ unsigned pk2(float a, float b) { f32x2_t v = {a, b}; bf16x2v_t r = __builtin_convertvector(v, bf16x2v_t); return __builtin_bit_cast(unsigned, r); }
; #define LAS __attribute__((address_space(3)))
; __device__ __forceinline__ int win_row(int n) {
;     if (n < 448) return n;
;     if (n < 960) return n + 64;
;     const int t = n - 960, q = t >> 9, ch = t & 511, qn = (q == 0) ? 0 : (q == 1) ? 2 : (q == 2) ? 3 : 1, cg = ch >> 6, ci = ch & 63;
;     return 1024 + 256 * cg + 128 * (qn >> 1) + 32 * (ci >> 4) + 16 * (qn & 1) + (ci & 15);
; }
; template <bool WINMAP = false>
; __device__ __forceinline__ void p0_transpose_item(const float* W, int N, bf16_t* WT, int ldt, int row_off, int col_off, LAS float* scr, int item, int lane, const float* gk = nullptr) {
;     const int nblk = N / 32, kb = item / nblk, nb = item % nblk, k0 = 64 * kb, n0 = 32 * nb;
;     { f32x4 v[8];
; #pragma unroll
;       for (int i = 0; i < 8; ++i) v[i] = *(const f32x4*)(W + (size_t)(k0 + 8 * i + (lane >> 3)) * N + n0 + 4 * (lane & 7));
; #pragma unroll
;       for (int i = 0; i < 8; ++i) { const int kk = 8 * i + (lane >> 3); const float gg = gk ? gk[k0 + kk] : 1.f; LAS float* d = scr + kk * 33 + 4 * (lane & 7);
;           d[0] = v[i][0] * gg; d[1] = v[i][1] * gg; d[2] = v[i][2] * gg; d[3] = v[i][3] * gg; } }
;     asm volatile("s_waitcnt lgkmcnt(0)" ::: "memory");
;     const int c = lane & 7;
; #pragma unroll
;     for (int j = 0; j < 4; ++j) { const int n = (lane >> 3) + 8 * j; const LAS float* s = scr + (8 * c) * 33 + n;
;         u32x4 o; o.x = pk2(s[0 * 33], s[1 * 33]); o.y = pk2(s[2 * 33], s[3 * 33]); o.z = pk2(s[4 * 33], s[5 * 33]); o.w = pk2(s[6 * 33], s[7 * 33]);
;         *(u32x4*)(WT + (size_t)(WINMAP ? win_row(n0 + n) : row_off + n0 + n) * ldt + col_off + k0 + 8 * c) = o; }
; __device__ __forceinline__ void phase0(const Args& a, LAS unsigned char* lds, int gw_, int NGW, int wave, int lane_) {
;     ...
;         if (r < I_IN) { p0_transpose_item<true>(a.w_in, INTOT, WinT, DM, 0, 0, scr, r, lane); continue; } r -= I_IN;
.LBB0_48:
	s_andn2_b64 vcc, exec, s[0:1]
	s_cbranch_vccnz .LBB0_21
	s_mul_hi_i32 s0, s30, 0xae4c415d
	s_add_i32 s0, s0, s30
	s_lshr_b32 s1, s0, 31
	s_ashr_i32 s4, s0, 6
	s_add_i32 s4, s4, s1
	s_mul_i32 s1, s4, 0xfffff440
	s_lshl_b32 s0, s4, 6
	s_add_i32 s14, s3, s1
	v_add_u32_e32 v30, s0, v53
	s_ashr_i32 s15, s14, 31
	v_lshl_add_u64 v[28:29], s[14:15], 2, v[46:47]
	v_add_u32_e32 v2, 8, v30
	v_add_u32_e32 v8, 16, v30
	v_add_u32_e32 v10, 24, v30
	v_add_u32_e32 v16, 32, v30
	v_add_u32_e32 v18, 40, v30
	v_mad_i64_i32 v[0:1], s[16:17], v30, s26, v[28:29]
	v_mad_i64_i32 v[4:5], s[16:17], v2, s26, v[28:29]
	v_mad_i64_i32 v[8:9], s[16:17], v8, s26, v[28:29]
	v_mad_i64_i32 v[12:13], s[16:17], v10, s26, v[28:29]
	v_mad_i64_i32 v[16:17], s[16:17], v16, s26, v[28:29]
	v_mad_i64_i32 v[20:21], s[16:17], v18, s26, v[28:29]
	global_load_dwordx4 v[0:3], v[0:1], off nt
	s_nop 0
	global_load_dwordx4 v[4:7], v[4:5], off nt
	s_nop 0
	global_load_dwordx4 v[8:11], v[8:9], off nt
	s_nop 0
	global_load_dwordx4 v[12:15], v[12:13], off nt
	s_nop 0
	global_load_dwordx4 v[16:19], v[16:17], off nt
	s_nop 0
	global_load_dwordx4 v[20:23], v[20:21], off nt
	v_add_u32_e32 v24, 48, v30
	v_mad_i64_i32 v[24:25], s[16:17], v24, s26, v[28:29]
	global_load_dwordx4 v[24:27], v[24:25], off nt
	v_add_u32_e32 v30, 56, v30
	v_mad_i64_i32 v[28:29], s[16:17], v30, s26, v[28:29]
	global_load_dwordx4 v[28:31], v[28:29], off nt
	s_mul_i32 s1, s4, 0x5e
	s_sub_i32 s1, s30, s1
	s_lshl_b32 s31, s1, 5
	s_waitcnt vmcnt(7)
	ds_write2_b32 v65, v0, v1 offset1:1
	ds_write2_b32 v65, v2, v3 offset0:2 offset1:3
	s_waitcnt vmcnt(6)
	ds_write2_b32 v66, v4, v5 offset1:1
	ds_write2_b32 v67, v6, v7 offset1:1
	s_waitcnt vmcnt(5)
	ds_write2_b32 v68, v8, v9 offset1:1
	ds_write2_b32 v69, v10, v11 offset1:1
	s_waitcnt vmcnt(4)
	ds_write2_b32 v70, v12, v13 offset1:1
	ds_write2_b32 v71, v14, v15 offset1:1
	s_waitcnt vmcnt(3)
	ds_write2_b32 v72, v16, v17 offset1:1
	ds_write2_b32 v73, v18, v19 offset1:1
	s_waitcnt vmcnt(2)
	ds_write2_b32 v74, v20, v21 offset1:1
	ds_write2_b32 v75, v22, v23 offset1:1
	s_waitcnt vmcnt(1)
	ds_write2_b32 v76, v24, v25 offset1:1
	ds_write2_b32 v77, v26, v27 offset1:1
	s_waitcnt vmcnt(0)
	ds_write2_b32 v78, v28, v29 offset1:1
	ds_write2_b32 v79, v30, v31 offset1:1
	s_waitcnt lgkmcnt(0)
	ds_read2_b32 v[2:3], v58 offset1:33
	ds_read2_b32 v[4:5], v58 offset0:66 offset1:99
	ds_read2_b32 v[6:7], v58 offset0:132 offset1:165
	ds_read2_b32 v[8:9], v58 offset0:198 offset1:231
	v_add_u32_e32 v12, s14, v53
	v_add_u32_e32 v10, s31, v53
	v_cmp_lt_i32_e32 vcc, s27, v12
	s_and_saveexec_b64 s[14:15], vcc
	s_cbranch_execz .LBB0_55
	v_cmp_lt_u32_e32 vcc, s28, v12
	s_and_saveexec_b64 s[16:17], vcc
	s_xor_b64 s[16:17], exec, s[16:17]
	s_cbranch_execz .LBB0_52
	v_add_u32_e32 v0, 0xfffffc40, v12
	v_lshrrev_b32_e32 v1, 9, v0
	v_cmp_eq_u32_e32 vcc, 2, v1
	s_mul_i32 s1, s4, 0xffffd100
	v_and_b32_e32 v11, 0x60, v64
	v_cndmask_b32_e64 v10, 1, 3, vcc
	v_cmp_ne_u32_e32 vcc, 1, v1
	s_nop 1
	v_cndmask_b32_e32 v1, 2, v10, vcc
	v_cmp_lt_u32_e32 vcc, s29, v0
	s_nop 1
	v_cndmask_b32_e32 v0, 0, v1, vcc
	v_add_u32_e32 v1, s1, v63
	v_add_u32_e32 v1, 0xfffff100, v1
	v_lshlrev_b32_e32 v10, 6, v0
	v_and_b32_e32 v1, 0x700, v1
	v_and_b32_e32 v10, 0x80, v10
	v_lshlrev_b32_e32 v0, 4, v0
	v_or3_b32 v1, v1, v10, v11
	v_and_b32_e32 v0, 16, v0
	v_or3_b32 v0, v1, v0, v60
	v_add_u32_e32 v10, 0x400, v0

; __device__ __forceinline__ void phase4a(const Args& a, int gw, int NGW, int lane_) {
;     int lane = lane_; asm volatile("" : "+v"(lane));
;     const bf16_t* PROJ = (const bf16_t*)(a.ws + WS_PROJ); const bf16_t* RAW = (const bf16_t*)(a.ws + WS_QKVRAW);
;     bf16_t* Q = (bf16_t*)(a.ws + WS_XN); bf16_t* K = (bf16_t*)(a.ws + WS_K);
;     const float gq0 = a.g_q[lane], gq1 = a.g_q[lane + 64], gq2 = a.g_q[lane + 128];
;     const float gk0 = a.g_k[lane], gk1 = a.g_k[lane + 64], gk2 = a.g_k[lane + 128];
;     const int fi = lane & 31; const float inv_freq = 1.0f / powf(10000.0f, (float)(2 * fi) / 64.0f);
;     const float qscale = 0.07216878364870322f * 1.4426950408889634f;
;     const float sgn = (lane < 32) ? -1.f : 1.f;
;     TokIn cur, nxt; int m = gw;
;     if (m < T) p4_load(cur, PROJ, RAW, a.pos, m, lane);
.LBB0_378:
	s_or_b64 exec, exec, s[0:1]
	s_add_u32 s0, s82, 0xd000000
	s_addc_u32 s1, s83, 0
	v_writelane_b32 v255, s0, 32
	s_waitcnt lgkmcnt(0)
	v_mov_b32_e32 v0, v224
	s_andn2_b64 vcc, exec, s[12:13]
	v_writelane_b32 v255, s1, 33
	s_barrier
	s_cbranch_vccnz .LBB0_387
	v_ashrrev_i32_e32 v1, 31, v0
	v_readlane_b32 s0, v255, 16
	v_lshlrev_b64 v[2:3], 2, v[0:1]
	v_readlane_b32 s2, v255, 18
	v_readlane_b32 s3, v255, 19
	v_readlane_b32 s4, v255, 20
	v_readlane_b32 s5, v255, 21
	v_lshl_add_u64 v[4:5], s[2:3], 0, v[2:3]
	s_mov_b32 s0, 0x3f2aaaab
	v_lshl_add_u64 v[6:7], s[4:5], 0, v[2:3]
	v_lshlrev_b32_e32 v2, 1, v0
	v_and_b32_e32 v3, 62, v2
	v_cvt_f32_ubyte0_e32 v3, v3
	v_mul_f32_e32 v32, 0x3c800000, v3
	v_mov_b32_e32 v3, 0x461c4000
	v_cmp_eq_f32_e32 vcc, 0, v32
	v_readlane_b32 s1, v255, 17
	s_mov_b32 s1, 0x42b17218
	v_cndmask_b32_e64 v3, v3, 1.0, vcc
	v_frexp_mant_f32_e32 v8, v3
	v_cmp_gt_f32_e32 vcc, s0, v8
	s_mov_b32 s0, 0x3f317218
	s_mov_b32 s2, 0x3fb8aa3b
	v_cndmask_b32_e64 v9, 1.0, 2.0, vcc
	v_mul_f32_e32 v8, v8, v9
	v_add_f32_e32 v11, 1.0, v8
	v_rcp_f32_e32 v16, v11
	v_add_f32_e32 v9, -1.0, v11
	v_sub_f32_e32 v13, v8, v9
	v_add_f32_e32 v9, -1.0, v8
	v_mul_f32_e32 v17, v9, v16
	v_mul_f32_e32 v10, v11, v17
	v_fma_f32 v12, v17, v11, -v10
	v_fmac_f32_e32 v12, v17, v13
	v_add_f32_e32 v8, v10, v12
	v_sub_f32_e32 v11, v9, v8
	v_pk_add_f32 v[14:15], v[8:9], v[10:11] neg_lo:[0,1] neg_hi:[0,1]
	v_mov_b32_e32 v13, v8
	v_pk_add_f32 v[8:9], v[14:15], v[12:13] neg_lo:[0,1] neg_hi:[0,1]
	v_mov_b32_e32 v12, 0x3e91f4c4
	v_add_f32_e32 v8, v8, v9
	v_add_f32_e32 v8, v11, v8
	v_mul_f32_e32 v9, v16, v8
	v_add_f32_e32 v8, v17, v9
	v_sub_f32_e32 v10, v8, v17
	v_sub_f32_e32 v18, v9, v10
	v_mul_f32_e32 v9, v8, v8
	v_fma_f32 v11, v8, v8, -v9
	v_add_f32_e32 v10, v18, v18
	v_fmac_f32_e32 v11, v8, v10
	v_add_f32_e32 v10, v9, v11
	v_fmac_f32_e32 v12, 0x3e76c4e1, v10
	v_fmaak_f32 v12, v10, v12, 0x3ecccdef
	v_sub_f32_e32 v9, v10, v9
	v_sub_f32_e32 v19, v11, v9
	v_mul_f32_e32 v9, v10, v12
	v_fma_f32 v11, v10, v12, -v9
	v_fmac_f32_e32 v11, v19, v12
	v_add_f32_e32 v12, v9, v11
	v_add_f32_e32 v13, 0x3f2aaaaa, v12
	v_sub_f32_e32 v9, v12, v9
	v_sub_f32_e32 v9, v11, v9
	v_add_f32_e32 v11, 0xbf2aaaaa, v13
	v_add_f32_e32 v9, 0x31739010, v9
	v_sub_f32_e32 v11, v12, v11
	v_pk_mul_f32 v[14:15], v[8:9], v[10:11]
	v_pk_add_f32 v[16:17], v[8:9], v[10:11]
	v_fma_f32 v12, v10, v8, -v14
	v_fmac_f32_e32 v12, v10, v18
	v_mov_b32_e32 v15, v17
	v_fmac_f32_e32 v12, v19, v8
	v_pk_add_f32 v[10:11], v[14:15], v[12:13]
	s_mov_b32 s4, 0x7f800000
	v_sub_f32_e32 v9, v10, v14
	v_sub_f32_e32 v9, v12, v9
	v_sub_f32_e32 v12, v13, v11
	v_add_f32_e32 v15, v17, v12
	v_cvt_f64_f32_e32 v[16:17], v3
	v_frexp_exp_i32_f64_e32 v3, v[16:17]
	v_subbrev_co_u32_e32 v3, vcc, 0, v3, vcc
	v_cvt_f32_i32_e32 v3, v3
	v_pk_mul_f32 v[12:13], v[10:11], v[10:11] op_sel:[0,1] op_sel_hi:[1,0]
	v_ldexp_f32 v17, v8, 1
	v_fma_f32 v14, v10, v11, -v12
	v_fmac_f32_e32 v14, v10, v15
	v_mul_f32_e32 v10, 0x3f317218, v3
	v_fmac_f32_e32 v14, v9, v11
	v_fma_f32 v9, v3, s0, -v10
	v_fmamk_f32 v16, v3, 0xb102e308, v9
	v_add_f32_e32 v11, v12, v14
	v_pk_add_f32 v[8:9], v[10:11], v[16:17]
	v_ldexp_f32 v3, v18, 1
	v_mov_b32_e32 v18, v11
	v_mov_b32_e32 v19, v9
	v_mov_b32_e32 v13, v17
	v_pk_add_f32 v[12:13], v[18:19], v[12:13] neg_lo:[0,1] neg_hi:[0,1]
	v_mov_b32_e32 v15, v11
	v_pk_add_f32 v[12:13], v[14:15], v[12:13] neg_lo:[0,1] neg_hi:[0,1]
	v_mov_b32_e32 v17, v8
	v_add_f32_e32 v3, v3, v12
	v_add_f32_e32 v11, v3, v13
	v_pk_add_f32 v[12:13], v[8:9], v[10:11] neg_lo:[0,1] neg_hi:[0,1]
	v_pk_add_f32 v[14:15], v[8:9], v[10:11]
	v_mov_b32_e32 v10, v11
	v_mov_b32_e32 v13, v15
	v_pk_add_f32 v[18:19], v[16:17], v[12:13] neg_lo:[0,1] neg_hi:[0,1]
	v_pk_add_f32 v[12:13], v[16:17], v[12:13]
	v_mov_b32_e32 v11, v8
	v_pk_add_f32 v[16:17], v[12:13], v[8:9] op_sel:[1,0] op_sel_hi:[0,1] neg_lo:[0,1] neg_hi:[0,1]
	v_pk_add_f32 v[20:21], v[14:15], v[16:17] op_sel_hi:[1,0] neg_lo:[0,1] neg_hi:[0,1]
	v_mov_b32_e32 v14, v15
	v_mov_b32_e32 v15, v13
	v_pk_mov_b32 v[16:17], v[8:9], v[16:17] op_sel:[1,0]
	v_mov_b32_e32 v20, v18
	v_pk_add_f32 v[14:15], v[14:15], v[16:17] neg_lo:[0,1] neg_hi:[0,1]
	v_mov_b32_e32 v19, v13
	v_pk_add_f32 v[8:9], v[10:11], v[14:15] neg_lo:[0,1] neg_hi:[0,1]
	s_movk_i32 s0, 0x204
	v_pk_add_f32 v[10:11], v[20:21], v[8:9]
	s_ashr_i32 s85, s84, 31
	v_pk_add_f32 v[14:15], v[10:11], v[10:11] op_sel:[0,1] op_sel_hi:[1,0]
	global_load_dword v26, v[6:7], off
	global_load_dword v27, v[6:7], off offset:256
	global_load_dword v28, v[6:7], off offset:512
	v_pk_add_f32 v[12:13], v[12:13], v[14:15] op_sel:[1,0] op_sel_hi:[0,1]
	v_mov_b32_e32 v11, v12
	v_pk_add_f32 v[16:17], v[10:11], v[18:19] neg_lo:[0,1] neg_hi:[0,1]
	v_mov_b32_e32 v9, v14
	v_sub_f32_e32 v3, v10, v16
	v_pk_add_f32 v[8:9], v[8:9], v[16:17] neg_lo:[0,1] neg_hi:[0,1]
	v_sub_f32_e32 v3, v18, v3
	v_add_f32_e32 v3, v8, v3
	v_add_f32_e32 v3, v3, v9
	v_add_f32_e32 v8, v12, v3
	v_sub_f32_e32 v9, v8, v12
	v_sub_f32_e32 v3, v3, v9
	v_mul_f32_e32 v9, v32, v8
	v_fma_f32 v8, v32, v8, -v9
	v_fmac_f32_e32 v8, v32, v3
	v_add_f32_e32 v3, v9, v8
	v_cmp_class_f32_e64 vcc, v9, s0
	v_sub_f32_e32 v10, v3, v9
	v_sub_f32_e32 v8, v8, v10
	v_cndmask_b32_e32 v3, v3, v9, vcc
	v_mov_b32_e32 v9, 0x37000000
	v_cmp_eq_f32_e32 vcc, s1, v3
	v_readlane_b32 s8, v255, 24
	v_readlane_b32 s9, v255, 25
	v_cndmask_b32_e32 v9, 0, v9, vcc
	v_sub_f32_e32 v10, v3, v9
	v_mul_f32_e32 v11, 0x3fb8aa3b, v10
	v_fma_f32 v12, v10, s2, -v11
	v_rndne_f32_e32 v13, v11
	v_fmamk_f32 v12, v10, 0x32a5705f, v12
; __device__ __forceinline__ unsigned pk2(float a, float b) { f32x2_t v = {a, b}; bf16x2v_t r = __builtin_convertvector(v, bf16x2v_t); return __builtin_bit_cast(unsigned, r); }
; __device__ __forceinline__ void p4_load(TokIn& t, const bf16_t* PROJ, const bf16_t* RAW, const int* pos, int m, int lane) {
;     const bf16_t* pr = PROJ + (size_t)m * PP; const bf16_t* rr = RAW + (size_t)m * UPN;
; #pragma unroll
;     for (int h = 0; h < NH; ++h) {
; #pragma unroll
;         for (int i = 0; i < 3; ++i) t.q[h][i] = rr[h * QKD + lane + 64 * i];
; #pragma unroll
;         for (int i = 0; i < 2; ++i) t.k[h][i] = rr[768 + h * 256 + lane + 64 * i];
;     }
;     t.kpe = pr[C_KPE + lane]; t.cq = *(const u32x2*)(pr + C_CQ + 4 * lane); t.ckv = *(const unsigned*)(pr + C_CKV + 2 * lane); t.pos = pos[m];
; }
; __device__ __forceinline__ unsigned short bf16r(float v) { return (unsigned short)(pk2(v, 0.f) & 0xffffu); }
; __device__ __forceinline__ void phase4a(const Args& a, int gw, int NGW, int lane_) {
;     int lane = lane_; asm volatile("" : "+v"(lane));
;     const bf16_t* PROJ = (const bf16_t*)(a.ws + WS_PROJ); const bf16_t* RAW = (const bf16_t*)(a.ws + WS_QKVRAW);
;     bf16_t* Q = (bf16_t*)(a.ws + WS_XN); bf16_t* K = (bf16_t*)(a.ws + WS_K);
;     const float gq0 = a.g_q[lane], gq1 = a.g_q[lane + 64], gq2 = a.g_q[lane + 128];
;     const float gk0 = a.g_k[lane], gk1 = a.g_k[lane + 64], gk2 = a.g_k[lane + 128];
;     const int fi = lane & 31; const float inv_freq = 1.0f / powf(10000.0f, (float)(2 * fi) / 64.0f);
;     const float qscale = 0.07216878364870322f * 1.4426950408889634f;
;     const float sgn = (lane < 32) ? -1.f : 1.f;
;     TokIn cur, nxt; int m = gw;
;     if (m < T) p4_load(cur, PROJ, RAW, a.pos, m, lane);
	v_sub_f32_e32 v11, v11, v13
	v_add_f32_e32 v11, v11, v12
	v_exp_f32_e32 v11, v11
	v_cvt_i32_f32_e32 v12, v13
	v_cmp_neq_f32_e64 vcc, |v3|, s4
	s_mov_b32 s2, 0xc2ce8ed0
	v_readlane_b32 s10, v255, 26
	v_cndmask_b32_e32 v3, 0, v8, vcc
	v_ldexp_f32 v8, v11, v12
	v_cmp_ngt_f32_e32 vcc, s2, v10
	v_add_f32_e32 v3, v9, v3
	v_mov_b32_e32 v9, 0x7f800000
	v_cndmask_b32_e32 v8, 0, v8, vcc
	v_cmp_nlt_f32_e32 vcc, s1, v10
	v_lshlrev_b64 v[12:13], 1, v[0:1]
	v_readlane_b32 s11, v255, 27
	v_cndmask_b32_e32 v8, v9, v8, vcc
	v_fma_f32 v3, v8, v3, v8
	v_cmp_class_f32_e64 vcc, v8, s0
	v_readlane_b32 s12, v255, 28
	v_readlane_b32 s13, v255, 29
	v_cndmask_b32_e32 v14, v3, v8, vcc
	v_and_b32_e32 v15, 0x7fffffff, v14
	v_div_scale_f32 v33, s[0:1], v15, v15, 1.0
	s_mul_i32 s0, s84, 0xe00
	s_mul_hi_i32 s1, s84, 0xe00
	s_add_u32 s0, s64, s0
	s_addc_u32 s1, s65, s1
	v_lshl_add_u64 v[6:7], s[0:1], 0, v[12:13]
	s_lshl_b64 s[0:1], s[84:85], 12
	s_add_u32 s0, s46, s0
	s_addc_u32 s1, s47, s1
	global_load_ushort v23, v[6:7], off offset:1536 nt
	global_load_ushort v22, v[6:7], off offset:1664 nt
	global_load_ushort v21, v[6:7], off offset:2048 nt
	global_load_ushort v20, v[6:7], off offset:2176 nt
	global_load_ushort v19, v[6:7], off offset:1024 nt
	global_load_ushort v18, v[6:7], off offset:1152 nt
	global_load_ushort v40, v[6:7], off offset:1280 nt
	global_load_ushort v41, v[6:7], off offset:1408 nt
	global_load_dword v29, v[4:5], off
	global_load_dword v30, v[4:5], off offset:256
	global_load_dword v31, v[4:5], off offset:512
	global_load_ushort v78, v[6:7], off nt
	global_load_ushort v77, v[6:7], off offset:128 nt
	global_load_ushort v76, v[6:7], off offset:256 nt
	global_load_ushort v75, v[6:7], off offset:384 nt
	global_load_ushort v74, v[6:7], off offset:512 nt
	global_load_ushort v73, v[6:7], off offset:640 nt
	global_load_ushort v71, v[6:7], off offset:768 nt
	global_load_ushort v70, v[6:7], off offset:896 nt
	v_lshl_add_u64 v[4:5], s[0:1], 0, v[12:13]
	v_ashrrev_i32_e32 v3, 31, v2
	v_readlane_b32 s14, v255, 30
	v_readlane_b32 s15, v255, 31
	v_mad_i64_i32 v[8:9], s[2:3], v0, 6, v[4:5]
	v_lshl_add_u64 v[10:11], v[2:3], 1, s[0:1]
	global_load_ushort v82, v[6:7], off offset:2560 nt
	global_load_ushort v72, v[6:7], off offset:2688 nt
	global_load_ushort v25, v[6:7], off offset:3072 nt
	global_load_ushort v24, v[6:7], off offset:3200 nt
	global_load_ushort v79, v[4:5], off offset:768 nt
	global_load_dwordx2 v[16:17], v[8:9], off
	global_load_dword v80, v[10:11], off offset:512
	v_readlane_b32 s8, v255, 0
	s_lshl_b64 s[0:1], s[84:85], 2
	v_readlane_b32 s12, v255, 4
	v_readlane_b32 s13, v255, 5
	s_add_u32 s0, s12, s0
	s_addc_u32 s1, s13, s1
	v_mov_b32_e32 v5, 0
	global_load_dword v4, v5, s[0:1]
	v_rcp_f32_e32 v34, v33
	v_readlane_b32 s9, v255, 1
	v_readlane_b32 s10, v255, 2
	v_readlane_b32 s11, v255, 3
	v_fma_f32 v6, -v33, v34, 1.0
	v_fmac_f32_e32 v34, v6, v34
	v_div_scale_f32 v6, vcc, 1.0, v15, 1.0
	v_mul_f32_e32 v7, v6, v34
	v_fma_f32 v8, -v33, v7, v6
	v_fmac_f32_e32 v7, v8, v34
	v_fma_f32 v6, -v33, v7, v6
	v_mbcnt_lo_u32_b32 v8, -1, 0
	v_div_fmas_f32 v6, v6, v34, v7
	v_mbcnt_hi_u32_b32 v8, -1, v8
	v_div_fixup_f32 v6, v6, |v14|, 1.0
	v_cmp_neq_f32_e32 vcc, s4, v32
	v_and_b32_e32 v9, 64, v8
	v_add_u32_e32 v9, 64, v9
	v_cndmask_b32_e32 v32, 0, v6, vcc
	v_cmp_gt_i32_e32 vcc, 32, v0
	v_xor_b32_e32 v10, 32, v8
	v_mad_i64_i32 v[6:7], s[0:1], v0, 6, 0
	v_cndmask_b32_e64 v33, 1.0, -1.0, vcc
	v_cmp_lt_i32_e32 vcc, v10, v9
	v_readlane_b32 s0, v255, 32
	v_readlane_b32 s14, v255, 6
	v_cndmask_b32_e32 v10, v8, v10, vcc
	v_lshlrev_b32_e32 v34, 2, v10
	v_xor_b32_e32 v10, 1, v8
	v_cmp_lt_i32_e32 vcc, v10, v9
	v_readlane_b32 s15, v255, 7
	v_readlane_b32 s16, v255, 8
	v_cndmask_b32_e32 v10, v8, v10, vcc
	v_lshlrev_b32_e32 v35, 2, v10
	v_xor_b32_e32 v10, 2, v8
	v_cmp_lt_i32_e32 vcc, v10, v9
	v_readlane_b32 s17, v255, 9
	s_mov_b32 s2, 0x5040100
	v_cndmask_b32_e32 v10, v8, v10, vcc
	v_lshlrev_b32_e32 v36, 2, v10
	v_xor_b32_e32 v10, 4, v8
	v_cmp_lt_i32_e32 vcc, v10, v9
	v_readlane_b32 s1, v255, 33
	s_brev_b32 s12, 60
	v_cndmask_b32_e32 v10, v8, v10, vcc
	v_lshlrev_b32_e32 v37, 2, v10
	v_xor_b32_e32 v10, 8, v8
	v_cmp_lt_i32_e32 vcc, v10, v9
	s_brev_b32 s3, 18
	s_waitcnt vmcnt(19)
	v_perm_b32 v89, v40, v41, s2
	v_cndmask_b32_e32 v10, v8, v10, vcc
	v_lshlrev_b32_e32 v38, 2, v10
	v_xor_b32_e32 v10, 16, v8
	v_cmp_lt_i32_e32 vcc, v10, v9
	s_mov_b32 s8, 0x800000
	s_mov_b32 s9, 0xfe5163ab
	v_cndmask_b32_e32 v8, v8, v10, vcc
	v_lshlrev_b32_e32 v39, 2, v8
	v_lshl_add_u64 v[8:9], s[64:65], 0, v[12:13]
	v_lshl_add_u64 v[10:11], s[94:95], 0, v[12:13]
	v_lshl_add_u64 v[12:13], s[0:1], 0, v[12:13]
	s_mov_b32 s10, 0x3c439041
	s_mov_b32 s11, 0xdb629599
	s_mov_b32 s15, 0xf534ddc0
	s_mov_b32 s17, 0xfc2757d1
	s_mov_b32 s24, 0x4e441529
	s_mov_b32 s25, 0xa2f9836e
	s_mov_b32 s26, 0x3fc90fda
	s_mov_b32 s27, 0x3f22f983
	s_mov_b32 s28, 0xbfc90fda
	s_mov_b32 s13, 0x3b800000
	v_mov_b32_e32 v40, 0x358637bd
	s_mov_b32 s14, 0x358637bd
	v_mov_b32_e32 v41, 0x3c0881c4
	v_mov_b32_e32 v42, 0xbab64f3b
	s_brev_b32 s29, 1
	s_movk_i32 s30, 0x1f8
	s_mov_b32 s16, 0x3baaaaab
	v_mov_b32_e32 v43, 0xe00
	v_not_b32_e32 v44, 63
	v_not_b32_e32 v45, 31
	v_mov_b32_e32 v46, 0x7fc00000
	v_mov_b32_e32 v47, 0x180
	s_mov_b32 s31, s84
	v_readlane_b32 s6, v255, 22
	v_readlane_b32 s7, v255, 23
	v_readlane_b32 s18, v255, 10
	v_readlane_b32 s19, v255, 11
	v_readlane_b32 s20, v255, 12
	v_readlane_b32 s21, v255, 13
	v_readlane_b32 s22, v255, 14
	v_readlane_b32 s23, v255, 15
	s_branch .LBB0_381

; __device__ __forceinline__ unsigned pk2(float a, float b) { f32x2_t v = {a, b}; bf16x2v_t r = __builtin_convertvector(v, bf16x2v_t); return __builtin_bit_cast(unsigned, r); }
; __device__ __forceinline__ void p4_load(TokIn& t, const bf16_t* PROJ, const bf16_t* RAW, const int* pos, int m, int lane) {
;     const bf16_t* pr = PROJ + (size_t)m * PP; const bf16_t* rr = RAW + (size_t)m * UPN;
; #pragma unroll
;     for (int h = 0; h < NH; ++h) {
; #pragma unroll
;         for (int i = 0; i < 3; ++i) t.q[h][i] = rr[h * QKD + lane + 64 * i];
; #pragma unroll
;         for (int i = 0; i < 2; ++i) t.k[h][i] = rr[768 + h * 256 + lane + 64 * i];
;     }
;     t.kpe = pr[C_KPE + lane]; t.cq = *(const u32x2*)(pr + C_CQ + 4 * lane); t.ckv = *(const unsigned*)(pr + C_CKV + 2 * lane); t.pos = pos[m];
; }
; __device__ __forceinline__ unsigned short bf16r(float v) { return (unsigned short)(pk2(v, 0.f) & 0xffffu); }
; __device__ __forceinline__ void phase4a(const Args& a, int gw, int NGW, int lane_) {
;     int lane = lane_; asm volatile("" : "+v"(lane));
;     const bf16_t* PROJ = (const bf16_t*)(a.ws + WS_PROJ); const bf16_t* RAW = (const bf16_t*)(a.ws + WS_QKVRAW);
;     bf16_t* Q = (bf16_t*)(a.ws + WS_XN); bf16_t* K = (bf16_t*)(a.ws + WS_K);
;     const float gq0 = a.g_q[lane], gq1 = a.g_q[lane + 64], gq2 = a.g_q[lane + 128];
;     const float gk0 = a.g_k[lane], gk1 = a.g_k[lane + 64], gk2 = a.g_k[lane + 128];
;     const int fi = lane & 31; const float inv_freq = 1.0f / powf(10000.0f, (float)(2 * fi) / 64.0f);
;     const float qscale = 0.07216878364870322f * 1.4426950408889634f;
;     const float sgn = (lane < 32) ? -1.f : 1.f;
;     TokIn cur, nxt; int m = gw;
;     if (m < T) p4_load(cur, PROJ, RAW, a.pos, m, lane);
;     for (; m < T; m += NGW) {
;         const int mn = m + NGW; if (mn < T) p4_load(nxt, PROJ, RAW, a.pos, mn, lane);
.LBB0_381:
	s_add_i32 s18, s31, s86
	s_cmpk_gt_i32 s18, 0x3fff
	s_cselect_b64 s[20:21], -1, 0
	s_and_b64 vcc, exec, s[20:21]
	s_cbranch_vccnz .LBB0_383
	s_ashr_i32 s19, s18, 31
	v_mad_i64_i32 v[14:15], s[0:1], s18, v43, v[8:9]
	s_lshl_b64 s[0:1], s[18:19], 12
	s_add_u32 s0, s46, s0
	s_addc_u32 s1, s47, s1
	v_lshl_add_u64 v[68:69], v[0:1], 1, s[0:1]
	global_load_ushort v48, v[14:15], off nt
	global_load_ushort v49, v[14:15], off offset:128 nt
	global_load_ushort v50, v[14:15], off offset:256 nt
	global_load_ushort v51, v[14:15], off offset:384 nt
	global_load_ushort v52, v[14:15], off offset:512 nt
	global_load_ushort v53, v[14:15], off offset:640 nt
	global_load_ushort v54, v[14:15], off offset:768 nt
	global_load_ushort v55, v[14:15], off offset:896 nt
	global_load_ushort v56, v[14:15], off offset:1536 nt
	global_load_ushort v58, v[14:15], off offset:1664 nt
	global_load_ushort v59, v[14:15], off offset:2048 nt
	global_load_ushort v61, v[14:15], off offset:2176 nt
	global_load_ushort v57, v[14:15], off offset:1024 nt
	global_load_ushort v60, v[14:15], off offset:1152 nt
	global_load_ushort v81, v[14:15], off offset:1280 nt
	global_load_ushort v83, v[14:15], off offset:1408 nt
	v_lshl_add_u64 v[84:85], v[68:69], 0, v[6:7]
	v_lshl_add_u64 v[86:87], v[2:3], 1, s[0:1]
	global_load_ushort v63, v[14:15], off offset:2560 nt
	global_load_ushort v64, v[14:15], off offset:2688 nt
	global_load_ushort v65, v[14:15], off offset:3072 nt
	global_load_ushort v66, v[14:15], off offset:3200 nt
	global_load_ushort v67, v[68:69], off offset:768 nt
	s_nop 0
	global_load_dwordx2 v[14:15], v[84:85], off
	global_load_dword v62, v[86:87], off offset:512
	v_readlane_b32 s48, v255, 0
	v_readlane_b32 s52, v255, 4
	v_readlane_b32 s53, v255, 5
	s_lshl_b64 s[0:1], s[18:19], 2
	s_mov_b64 s[40:41], s[52:53]
	s_add_u32 s0, s40, s0
	s_addc_u32 s1, s41, s1
	global_load_dword v68, v5, s[0:1]
	v_readlane_b32 s49, v255, 1
	v_readlane_b32 s50, v255, 2
	v_readlane_b32 s51, v255, 3
	v_readlane_b32 s54, v255, 6
	v_readlane_b32 s55, v255, 7
	v_readlane_b32 s56, v255, 8
	v_readlane_b32 s57, v255, 9
	v_readlane_b32 s58, v255, 10
	v_readlane_b32 s59, v255, 11
	v_readlane_b32 s60, v255, 12
	v_readlane_b32 s61, v255, 13
	v_readlane_b32 s62, v255, 14
	v_readlane_b32 s63, v255, 15
	s_waitcnt vmcnt(8)
	v_perm_b32 v69, v81, v83, s2

; __device__ __forceinline__ unsigned pk2(float a, float b) { f32x2_t v = {a, b}; bf16x2v_t r = __builtin_convertvector(v, bf16x2v_t); return __builtin_bit_cast(unsigned, r); }
; __device__ __forceinline__ float bf1(unsigned short u) { return __uint_as_float(((unsigned)u) << 16); }
; #define LAS __attribute__((address_space(3)))
; __device__ __forceinline__ void phase4b(const Args& a, LAS unsigned char* lds, int tid_) {
;     ...
;         for (int i = 0; i < 8; ++i) { const int c = tid + 512 * i, tok = c >> 6, rem = c & 63, h = rem >> 4, part = rem & 15;
;             const u32x4 v = *(const u32x4*)(RAW + (size_t)(row0 + tok) * UPN + 768 + h * 256 + 128 + part * 8);
;             *(LAS u32x4*)(lds + tok * PITCH + (h * 128 + part * 8) * 2) = v; }
;         __syncthreads();
;         const int b = row0 / SEQ, s0 = row0 % SEQ, ch = tid & 7;
;         int key[8];
; #pragma unroll
;         for (int e = 0; e < 8; ++e) { const int p = ch * 8 + e, q = p & 15; key[e] = 16 * (p >> 4) + 8 * ((q & 7) >> 2) + 4 * (q >> 3) + (q & 3); }
;         float rk[8];
; #pragma unroll
;         for (int e = 0; e < 8; ++e) rk[e] = rkl[key[e]];
; #pragma unroll
;         for (int i = 0; i < 8; ++i) {
;             const int row = (tid >> 3) + 64 * i, h = row >> 7, d = row & 127;
;             unsigned w[4];
; #pragma unroll
;             for (int e = 0; e < 4; ++e) {
;                 const float lo = bf1(*(const LAS unsigned short*)(lds + key[2 * e] * PITCH + row * 2)) * rk[2 * e], hi = bf1(*(const LAS unsigned short*)(lds + key[2 * e + 1] * PITCH + row * 2)) * rk[2 * e + 1];
;                 w[e] = pk2(lo, hi);
;             }
;             *(u32x4*)(VT + ((size_t)(b * NH + h) * VD + d) * SEQ + s0 + ch * 8) = (u32x4){w[0], w[1], w[2], w[3]};
.LBB0_391:
	s_or_b64 exec, exec, s[0:1]
	v_add_u32_e32 v0, s8, v27
	v_mad_i64_i32 v[0:1], s[0:1], v0, s2, v[10:11]
	v_lshl_add_u64 v[0:1], v[0:1], 0, v[8:9]
	s_waitcnt lgkmcnt(4)
	v_add_co_u32_e32 v70, vcc, 0x9800000, v0
	v_add_u32_e32 v0, s8, v36
	s_nop 0
	v_addc_co_u32_e32 v71, vcc, 0, v1, vcc
	v_mad_i64_i32 v[0:1], s[0:1], v0, s2, v[10:11]
	v_lshl_add_u64 v[0:1], v[0:1], 0, v[8:9]
	v_add_co_u32_e32 v72, vcc, 0x9800000, v0
	s_waitcnt lgkmcnt(3)
	v_add_u32_e32 v23, s8, v37
	s_waitcnt lgkmcnt(2)
	v_addc_co_u32_e32 v73, vcc, 0, v1, vcc
	global_load_dwordx4 v[0:3], v[70:71], off offset:1792 nt
	global_load_dwordx4 v[4:7], v[72:73], off offset:1792 nt
	v_mad_i64_i32 v[70:71], s[0:1], v23, s2, v[10:11]
	v_lshl_add_u64 v[70:71], v[70:71], 0, v[8:9]
	v_add_co_u32_e32 v78, vcc, 0x9800000, v70
	v_add_u32_e32 v23, s8, v38
	s_nop 0
	v_addc_co_u32_e32 v79, vcc, 0, v71, vcc
	v_mad_i64_i32 v[70:71], s[0:1], v23, s2, v[10:11]
	v_lshl_add_u64 v[70:71], v[70:71], 0, v[8:9]
	v_add_co_u32_e32 v80, vcc, 0x9800000, v70
	v_add_u32_e32 v23, s8, v39
	s_nop 0
	v_addc_co_u32_e32 v81, vcc, 0, v71, vcc
	global_load_dwordx4 v[70:73], v[78:79], off offset:1792 nt
	s_waitcnt lgkmcnt(0)
	global_load_dwordx4 v[74:77], v[80:81], off offset:1792 nt
	v_mad_i64_i32 v[78:79], s[0:1], v23, s2, v[10:11]
	v_lshl_add_u64 v[78:79], v[78:79], 0, v[8:9]
	v_add_co_u32_e32 v86, vcc, 0x9800000, v78
	v_add_u32_e32 v23, s8, v40
	s_nop 0
	v_addc_co_u32_e32 v87, vcc, 0, v79, vcc
	v_mad_i64_i32 v[78:79], s[0:1], v23, s2, v[10:11]
	v_lshl_add_u64 v[78:79], v[78:79], 0, v[8:9]
	v_add_co_u32_e32 v88, vcc, 0x9800000, v78
	v_add_u32_e32 v23, s8, v41
	s_nop 0
	v_addc_co_u32_e32 v89, vcc, 0, v79, vcc
	global_load_dwordx4 v[78:81], v[86:87], off offset:1792 nt
	global_load_dwordx4 v[82:85], v[88:89], off offset:1792 nt
	v_mad_i64_i32 v[86:87], s[0:1], v23, s2, v[10:11]
	v_lshl_add_u64 v[86:87], v[86:87], 0, v[8:9]
	v_add_co_u32_e32 v94, vcc, 0x9800000, v86
	v_add_u32_e32 v23, s8, v42
	s_nop 0
	v_addc_co_u32_e32 v95, vcc, 0, v87, vcc
	v_mad_i64_i32 v[86:87], s[0:1], v23, s2, v[10:11]
	v_lshl_add_u64 v[86:87], v[86:87], 0, v[8:9]
	v_add_co_u32_e32 v96, vcc, 0x9800000, v86
	s_ashr_i32 s0, s14, 31
	s_nop 0
	v_addc_co_u32_e32 v97, vcc, 0, v87, vcc
	global_load_dwordx4 v[86:89], v[94:95], off offset:1792 nt
	global_load_dwordx4 v[90:93], v[96:97], off offset:1792 nt
	s_lshr_b32 s0, s0, 25
	s_add_i32 s0, s14, s0
	s_ashr_i32 s1, s0, 7
	s_ashr_i32 s0, s8, 31
	s_lshr_b32 s0, s0, 19
	s_add_i32 s0, s8, s0
	s_lshl_b32 s4, s1, 2
	s_and_b32 s0, s0, 0xffffe000
	s_sub_i32 s0, s8, s0
	s_ashr_i32 s1, s0, 31
	s_lshl_b64 s[0:1], s[0:1], 1
	s_add_i32 s14, s14, s88
	s_add_i32 s8, s8, s9
	s_cmpk_lt_i32 s14, 0x100
	s_waitcnt vmcnt(7)
	ds_write_b128 v54, v[0:3]
	s_waitcnt vmcnt(6)
	ds_write_b128 v55, v[4:7]
	s_waitcnt vmcnt(5)
	ds_write_b128 v56, v[70:73]
	s_waitcnt vmcnt(4)
	ds_write_b128 v57, v[74:77]
	s_waitcnt vmcnt(3)
	ds_write_b128 v58, v[78:81]
	s_waitcnt vmcnt(2)
	ds_write_b128 v59, v[82:85]
	s_waitcnt vmcnt(1)
	ds_write_b128 v60, v[86:89]
	s_waitcnt vmcnt(0)
	ds_write_b128 v61, v[90:93]
	s_waitcnt lgkmcnt(0)
	s_barrier
	ds_read_b128 v[0:3], v43
	ds_read_u16 v4, v62
	ds_read_u16 v5, v62 offset:1040
	ds_read_u16 v23, v62 offset:2080
	ds_read_u16 v25, v62 offset:3120
	ds_read_u16 v74, v62 offset:8320
	ds_read_u16 v75, v62 offset:9360
	ds_read_u16 v76, v62 offset:10400
	ds_read_u16 v77, v62 offset:11440
	s_waitcnt lgkmcnt(6)
	v_lshlrev_b32_e32 v71, 16, v5
	v_lshlrev_b32_e32 v70, 16, v4
	ds_read_b128 v[4:7], v44
	s_waitcnt lgkmcnt(5)
	v_lshlrev_b32_e32 v73, 16, v25
	v_lshlrev_b32_e32 v72, 16, v23
	v_pk_mul_f32 v[70:71], v[0:1], v[70:71]
	v_pk_mul_f32 v[72:73], v[2:3], v[72:73]
	v_cvt_pk_bf16_f32 v70, v70, v71
	v_cvt_pk_bf16_f32 v71, v72, v73
	s_waitcnt lgkmcnt(3)
	v_lshlrev_b32_e32 v73, 16, v75
	v_lshlrev_b32_e32 v72, 16, v74
	s_waitcnt lgkmcnt(1)
	v_lshlrev_b32_e32 v75, 16, v77
	v_lshlrev_b32_e32 v74, 16, v76
	s_waitcnt lgkmcnt(0)
	v_pk_mul_f32 v[72:73], v[4:5], v[72:73]
	v_pk_mul_f32 v[74:75], v[6:7], v[74:75]
	v_cvt_pk_bf16_f32 v72, v72, v73
	v_cvt_pk_bf16_f32 v73, v74, v75
	v_add_u32_e32 v74, s4, v45
	v_ashrrev_i32_e32 v75, 31, v74
	v_lshlrev_b64 v[74:75], 21, v[74:75]
	v_lshl_add_u64 v[74:75], v[12:13], 0, v[74:75]
	v_lshl_add_u64 v[74:75], v[74:75], 0, s[0:1]
	v_mov_b32_e32 v25, v9
	v_lshl_add_u64 v[74:75], v[74:75], 0, v[24:25]
	global_store_dwordx4 v[74:75], v[70:73], off
	ds_read_u16 v23, v63
	ds_read_u16 v70, v63 offset:1040
	ds_read_u16 v72, v63 offset:2080
	ds_read_u16 v73, v63 offset:3120
	ds_read_u16 v74, v63 offset:8320
	ds_read_u16 v75, v63 offset:9360
	ds_read_u16 v76, v63 offset:10400
	ds_read_u16 v77, v63 offset:11440
	s_waitcnt lgkmcnt(6)
	v_lshlrev_b32_e32 v71, 16, v70
	v_lshlrev_b32_e32 v70, 16, v23
	s_waitcnt lgkmcnt(4)
	v_lshlrev_b32_e32 v73, 16, v73
	v_lshlrev_b32_e32 v72, 16, v72
	v_pk_mul_f32 v[70:71], v[0:1], v[70:71]
	v_pk_mul_f32 v[72:73], v[2:3], v[72:73]
	v_cvt_pk_bf16_f32 v70, v70, v71
	v_cvt_pk_bf16_f32 v71, v72, v73
	s_waitcnt lgkmcnt(2)
	v_lshlrev_b32_e32 v73, 16, v75
	v_lshlrev_b32_e32 v72, 16, v74
	s_waitcnt lgkmcnt(0)
	v_lshlrev_b32_e32 v75, 16, v77
	v_lshlrev_b32_e32 v74, 16, v76
	v_pk_mul_f32 v[72:73], v[4:5], v[72:73]
	v_pk_mul_f32 v[74:75], v[6:7], v[74:75]
	v_cvt_pk_bf16_f32 v72, v72, v73
	v_cvt_pk_bf16_f32 v73, v74, v75
	v_add_u32_e32 v74, s4, v46
	v_ashrrev_i32_e32 v75, 31, v74
	v_lshlrev_b64 v[74:75], 21, v[74:75]
	v_lshl_add_u64 v[74:75], v[14:15], 0, v[74:75]
	v_lshl_add_u64 v[74:75], v[74:75], 0, s[0:1]
	v_lshl_add_u64 v[74:75], v[74:75], 0, v[24:25]
	global_store_dwordx4 v[74:75], v[70:73], off
	ds_read_u16 v23, v64
	ds_read_u16 v70, v64 offset:1040
	ds_read_u16 v72, v64 offset:2080
	ds_read_u16 v73, v64 offset:3120
	ds_read_u16 v74, v64 offset:8320
	ds_read_u16 v75, v64 offset:9360
	ds_read_u16 v76, v64 offset:10400
	ds_read_u16 v77, v64 offset:11440
	s_waitcnt lgkmcnt(6)
; __device__ __forceinline__ unsigned pk2(float a, float b) { f32x2_t v = {a, b}; bf16x2v_t r = __builtin_convertvector(v, bf16x2v_t); return __builtin_bit_cast(unsigned, r); }
; __device__ __forceinline__ float bf1(unsigned short u) { return __uint_as_float(((unsigned)u) << 16); }
; #define LAS __attribute__((address_space(3)))
; __device__ __forceinline__ void phase4b(const Args& a, LAS unsigned char* lds, int tid_) {
;     ...
;         for (int i = 0; i < 8; ++i) {
;             const int row = (tid >> 3) + 64 * i, h = row >> 7, d = row & 127;
;             unsigned w[4];
; #pragma unroll
;             for (int e = 0; e < 4; ++e) {
;                 const float lo = bf1(*(const LAS unsigned short*)(lds + key[2 * e] * PITCH + row * 2)) * rk[2 * e], hi = bf1(*(const LAS unsigned short*)(lds + key[2 * e + 1] * PITCH + row * 2)) * rk[2 * e + 1];
;                 w[e] = pk2(lo, hi);
;             }
;             *(u32x4*)(VT + ((size_t)(b * NH + h) * VD + d) * SEQ + s0 + ch * 8) = (u32x4){w[0], w[1], w[2], w[3]};
;         }
;         __syncthreads();
	v_lshlrev_b32_e32 v71, 16, v70
	v_lshlrev_b32_e32 v70, 16, v23
	s_waitcnt lgkmcnt(4)
	v_lshlrev_b32_e32 v73, 16, v73
	v_lshlrev_b32_e32 v72, 16, v72
	v_pk_mul_f32 v[70:71], v[0:1], v[70:71]
	v_pk_mul_f32 v[72:73], v[2:3], v[72:73]
	v_cvt_pk_bf16_f32 v70, v70, v71
	v_cvt_pk_bf16_f32 v71, v72, v73
	s_waitcnt lgkmcnt(2)
	v_lshlrev_b32_e32 v73, 16, v75
	v_lshlrev_b32_e32 v72, 16, v74
	s_waitcnt lgkmcnt(0)
	v_lshlrev_b32_e32 v75, 16, v77
	v_lshlrev_b32_e32 v74, 16, v76
	v_pk_mul_f32 v[72:73], v[4:5], v[72:73]
	v_pk_mul_f32 v[74:75], v[6:7], v[74:75]
	v_cvt_pk_bf16_f32 v72, v72, v73
	v_cvt_pk_bf16_f32 v73, v74, v75
	v_add_u32_e32 v74, s4, v47
	v_ashrrev_i32_e32 v75, 31, v74
	v_lshlrev_b64 v[74:75], 21, v[74:75]
	v_lshl_add_u64 v[74:75], v[12:13], 0, v[74:75]
	v_lshl_add_u64 v[74:75], v[74:75], 0, s[0:1]
	v_lshl_add_u64 v[74:75], v[74:75], 0, v[24:25]
	global_store_dwordx4 v[74:75], v[70:73], off
	ds_read_u16 v23, v65
	ds_read_u16 v70, v65 offset:1040
	ds_read_u16 v72, v65 offset:2080
	ds_read_u16 v73, v65 offset:3120
	ds_read_u16 v74, v65 offset:8320
	ds_read_u16 v75, v65 offset:9360
	ds_read_u16 v76, v65 offset:10400
	ds_read_u16 v77, v65 offset:11440
	s_waitcnt lgkmcnt(6)
	v_lshlrev_b32_e32 v71, 16, v70
	v_lshlrev_b32_e32 v70, 16, v23
	s_waitcnt lgkmcnt(4)
	v_lshlrev_b32_e32 v73, 16, v73
	v_lshlrev_b32_e32 v72, 16, v72
	v_pk_mul_f32 v[70:71], v[0:1], v[70:71]
	v_pk_mul_f32 v[72:73], v[2:3], v[72:73]
	v_cvt_pk_bf16_f32 v70, v70, v71
	v_cvt_pk_bf16_f32 v71, v72, v73
	s_waitcnt lgkmcnt(2)
	v_lshlrev_b32_e32 v73, 16, v75
	v_lshlrev_b32_e32 v72, 16, v74
	s_waitcnt lgkmcnt(0)
	v_lshlrev_b32_e32 v75, 16, v77
	v_lshlrev_b32_e32 v74, 16, v76
	v_pk_mul_f32 v[72:73], v[4:5], v[72:73]
	v_pk_mul_f32 v[74:75], v[6:7], v[74:75]
	v_cvt_pk_bf16_f32 v72, v72, v73
	v_cvt_pk_bf16_f32 v73, v74, v75
	v_add_u32_e32 v74, s4, v48
	v_ashrrev_i32_e32 v75, 31, v74
	v_lshlrev_b64 v[74:75], 21, v[74:75]
	v_lshl_add_u64 v[74:75], v[16:17], 0, v[74:75]
	v_lshl_add_u64 v[74:75], v[74:75], 0, s[0:1]
	v_lshl_add_u64 v[74:75], v[74:75], 0, v[24:25]
	global_store_dwordx4 v[74:75], v[70:73], off
	ds_read_u16 v23, v66
	ds_read_u16 v70, v66 offset:1040
	ds_read_u16 v72, v66 offset:2080
	ds_read_u16 v73, v66 offset:3120
	ds_read_u16 v74, v66 offset:8320
	ds_read_u16 v75, v66 offset:9360
	ds_read_u16 v76, v66 offset:10400
	ds_read_u16 v77, v66 offset:11440
	s_waitcnt lgkmcnt(6)
	v_lshlrev_b32_e32 v71, 16, v70
	v_lshlrev_b32_e32 v70, 16, v23
	s_waitcnt lgkmcnt(4)
	v_lshlrev_b32_e32 v73, 16, v73
	v_lshlrev_b32_e32 v72, 16, v72
	v_pk_mul_f32 v[70:71], v[0:1], v[70:71]
	v_pk_mul_f32 v[72:73], v[2:3], v[72:73]
	v_cvt_pk_bf16_f32 v70, v70, v71
	v_cvt_pk_bf16_f32 v71, v72, v73
	s_waitcnt lgkmcnt(2)
	v_lshlrev_b32_e32 v73, 16, v75
	v_lshlrev_b32_e32 v72, 16, v74
	s_waitcnt lgkmcnt(0)
	v_lshlrev_b32_e32 v75, 16, v77
	v_lshlrev_b32_e32 v74, 16, v76
	v_pk_mul_f32 v[72:73], v[4:5], v[72:73]
	v_pk_mul_f32 v[74:75], v[6:7], v[74:75]
	v_cvt_pk_bf16_f32 v72, v72, v73
	v_cvt_pk_bf16_f32 v73, v74, v75
	v_add_u32_e32 v74, s4, v49
	v_ashrrev_i32_e32 v75, 31, v74
	v_lshlrev_b64 v[74:75], 21, v[74:75]
	v_lshl_add_u64 v[74:75], v[12:13], 0, v[74:75]
	v_lshl_add_u64 v[74:75], v[74:75], 0, s[0:1]
	v_lshl_add_u64 v[74:75], v[74:75], 0, v[24:25]
	global_store_dwordx4 v[74:75], v[70:73], off
	ds_read_u16 v23, v67
	ds_read_u16 v70, v67 offset:1040
	ds_read_u16 v72, v67 offset:2080
	ds_read_u16 v73, v67 offset:3120
	ds_read_u16 v74, v67 offset:8320
	ds_read_u16 v75, v67 offset:9360
	ds_read_u16 v76, v67 offset:10400
	ds_read_u16 v77, v67 offset:11440
	s_waitcnt lgkmcnt(6)
	v_lshlrev_b32_e32 v71, 16, v70
	v_lshlrev_b32_e32 v70, 16, v23
	s_waitcnt lgkmcnt(4)
	v_lshlrev_b32_e32 v73, 16, v73
	v_lshlrev_b32_e32 v72, 16, v72
	v_pk_mul_f32 v[70:71], v[0:1], v[70:71]
	v_pk_mul_f32 v[72:73], v[2:3], v[72:73]
	v_cvt_pk_bf16_f32 v70, v70, v71
	v_cvt_pk_bf16_f32 v71, v72, v73
	s_waitcnt lgkmcnt(2)
	v_lshlrev_b32_e32 v73, 16, v75
	v_lshlrev_b32_e32 v72, 16, v74
	s_waitcnt lgkmcnt(0)
	v_lshlrev_b32_e32 v75, 16, v77
	v_lshlrev_b32_e32 v74, 16, v76
	v_pk_mul_f32 v[72:73], v[4:5], v[72:73]
	v_pk_mul_f32 v[74:75], v[6:7], v[74:75]
	v_cvt_pk_bf16_f32 v72, v72, v73
	v_cvt_pk_bf16_f32 v73, v74, v75
	v_add_u32_e32 v74, s4, v50
	v_ashrrev_i32_e32 v75, 31, v74
	v_lshlrev_b64 v[74:75], 21, v[74:75]
	v_lshl_add_u64 v[74:75], v[18:19], 0, v[74:75]
	v_lshl_add_u64 v[74:75], v[74:75], 0, s[0:1]
	v_lshl_add_u64 v[74:75], v[74:75], 0, v[24:25]
	global_store_dwordx4 v[74:75], v[70:73], off
	ds_read_u16 v23, v68
	ds_read_u16 v70, v68 offset:1040
	ds_read_u16 v72, v68 offset:2080
	ds_read_u16 v73, v68 offset:3120
	ds_read_u16 v74, v68 offset:8320
	ds_read_u16 v75, v68 offset:9360
	ds_read_u16 v76, v68 offset:10400
	ds_read_u16 v77, v68 offset:11440
	s_waitcnt lgkmcnt(6)
	v_lshlrev_b32_e32 v71, 16, v70
	v_lshlrev_b32_e32 v70, 16, v23
	s_waitcnt lgkmcnt(4)
	v_lshlrev_b32_e32 v73, 16, v73
	v_lshlrev_b32_e32 v72, 16, v72
	v_pk_mul_f32 v[70:71], v[0:1], v[70:71]
	v_pk_mul_f32 v[72:73], v[2:3], v[72:73]
	v_cvt_pk_bf16_f32 v70, v70, v71
	v_cvt_pk_bf16_f32 v71, v72, v73
	s_waitcnt lgkmcnt(2)
	v_lshlrev_b32_e32 v73, 16, v75
	v_lshlrev_b32_e32 v72, 16, v74
	s_waitcnt lgkmcnt(0)
	v_lshlrev_b32_e32 v75, 16, v77
	v_lshlrev_b32_e32 v74, 16, v76
	v_pk_mul_f32 v[72:73], v[4:5], v[72:73]
	v_pk_mul_f32 v[74:75], v[6:7], v[74:75]
	v_cvt_pk_bf16_f32 v72, v72, v73
	v_cvt_pk_bf16_f32 v73, v74, v75
	v_add_u32_e32 v74, s4, v51
	v_ashrrev_i32_e32 v75, 31, v74
	v_lshlrev_b64 v[74:75], 21, v[74:75]
	v_lshl_add_u64 v[74:75], v[12:13], 0, v[74:75]
	v_lshl_add_u64 v[74:75], v[74:75], 0, s[0:1]
	v_lshl_add_u64 v[74:75], v[74:75], 0, v[24:25]
	global_store_dwordx4 v[74:75], v[70:73], off
	ds_read_u16 v23, v69
	ds_read_u16 v70, v69 offset:1040
	ds_read_u16 v72, v69 offset:2080
	ds_read_u16 v73, v69 offset:3120
	ds_read_u16 v74, v69 offset:8320
	ds_read_u16 v75, v69 offset:9360
	ds_read_u16 v76, v69 offset:10400
	ds_read_u16 v77, v69 offset:11440
	s_waitcnt lgkmcnt(6)
	v_lshlrev_b32_e32 v71, 16, v70
	v_lshlrev_b32_e32 v70, 16, v23
	v_pk_mul_f32 v[0:1], v[0:1], v[70:71]
	s_waitcnt lgkmcnt(4)
	v_lshlrev_b32_e32 v71, 16, v73
	v_lshlrev_b32_e32 v70, 16, v72
	v_pk_mul_f32 v[2:3], v[2:3], v[70:71]
	v_cvt_pk_bf16_f32 v0, v0, v1
	v_cvt_pk_bf16_f32 v1, v2, v3
	s_waitcnt lgkmcnt(2)
	v_lshlrev_b32_e32 v3, 16, v75
	v_lshlrev_b32_e32 v2, 16, v74
	v_pk_mul_f32 v[2:3], v[4:5], v[2:3]
	s_waitcnt lgkmcnt(0)
	v_lshlrev_b32_e32 v5, 16, v77
	v_lshlrev_b32_e32 v4, 16, v76
	v_pk_mul_f32 v[4:5], v[6:7], v[4:5]
	v_cvt_pk_bf16_f32 v2, v2, v3
	v_cvt_pk_bf16_f32 v3, v4, v5
	v_add_u32_e32 v4, s4, v52
	v_ashrrev_i32_e32 v5, 31, v4
	v_lshlrev_b64 v[4:5], 21, v[4:5]
	v_lshl_add_u64 v[4:5], v[20:21], 0, v[4:5]
	v_lshl_add_u64 v[4:5], v[4:5], 0, s[0:1]
	v_lshl_add_u64 v[4:5], v[4:5], 0, v[24:25]
	global_store_dwordx4 v[4:5], v[0:3], off
	s_barrier
	s_cbranch_scc0 .LBB0_420

; __device__ __forceinline__ void unpack8(const u32x4 v, float (&f)[8]) { f[0] = bflo(v.x); f[1] = bfhi(v.x); f[2] = bflo(v.y); f[3] = bfhi(v.y); f[4] = bflo(v.z); f[5] = bfhi(v.z); f[6] = bflo(v.w); f[7] = bfhi(v.w); }
; __device__ __forceinline__ void phase6(const Args& a, int gw, int NGW, int lane_) {
;     int lane = lane_; asm volatile("" : "+v"(lane));
;     const bf16_t* PROJ = (const bf16_t*)(a.ws + WS_PROJ); const bf16_t* O = (const bf16_t*)(a.ws + WS_QKVRAW); bf16_t* Y = (bf16_t*)(a.ws + WS_XN);
;     const int c0 = 8 * lane;
;     float goa[8], goc[8], w0[8], w1[8], w2[8];
; #pragma unroll
;     for (int e = 0; e < 8; ++e) { goa[e] = a.g_oa[c0 + e]; goc[e] = a.g_oc[c0 + e]; w0[e] = a.conv_w[c0 + e]; w1[e] = a.conv_w[CW + c0 + e]; w2[e] = a.conv_w[2 * CW + c0 + e]; }
;     for (int ch = gw; ch < T / 8; ch += NGW) {
;         const int m0 = ch * 8, s0 = m0 % SEQ;
;         float pm2[8], pm1[8];
;         if (s0 >= 2) { unpack8(*(const u32x4*)(PROJ + (size_t)(m0 - 1) * PP + C_PR + c0), pm1); unpack8(*(const u32x4*)(PROJ + (size_t)(m0 - 2) * PP + C_PR + c0), pm2); }
;         else {
; #pragma unroll
;             for (int e = 0; e < 8; ++e) { pm1[e] = 0.f; pm2[e] = 0.f; }
;         }
;         Tok6 cur, nxt; p6_load(cur, PROJ, O, m0, c0);
; #pragma unroll 1
;         for (int i = 0; i < 8; ++i) {
;             const int m = m0 + i;
;             if (i < 7) p6_load(nxt, PROJ, O, m + 1, c0);
.LBB0_557:
	s_ashr_i32 s5, s4, 31
	s_lshl_b64 s[6:7], s[4:5], 12
	s_lshl_b64 s[4:5], s[4:5], 10
	v_lshl_add_u64 v[98:99], v[72:73], 0, s[4:5]
	v_lshl_add_u64 v[100:101], v[74:75], 0, s[6:7]
	global_load_dwordx4 v[64:67], v[98:99], off nt
	global_load_dwordx4 v[68:71], v[100:101], off offset:1024 nt
	global_load_dwordx4 v[60:63], v[100:101], off offset:2048 nt
	global_load_dwordx4 v[56:59], v[100:101], off offset:3072 nt
	s_mov_b32 s6, 0
	s_add_i32 s4, s1, s6
	s_cmp_eq_u32 s6, 7
	s_cbranch_scc1 .LBB0_559
.LBB0_558:
	s_add_i32 s8, s4, 1
	s_ashr_i32 s9, s8, 31
	s_lshl_b64 s[10:11], s[8:9], 12
	s_lshl_b64 s[8:9], s[8:9], 10
	v_lshl_add_u64 v[98:99], v[72:73], 0, s[8:9]
	v_lshl_add_u64 v[100:101], v[74:75], 0, s[10:11]
	global_load_dwordx4 v[40:43], v[98:99], off nt
	global_load_dwordx4 v[44:47], v[100:101], off offset:1024 nt
	global_load_dwordx4 v[48:51], v[100:101], off offset:2048 nt
	global_load_dwordx4 v[52:55], v[100:101], off offset:3072 nt

;     __device__ __forceinline__ void operator()(const f32x4 (&acc)[2][2][4][2], const Unit& u, int wr, int wc, int fr, int fq) const {
;         const int row0 = u.pm * BM + wr * 64 + fr; const int col0 = u.pn * BM + wc * 32 + 8 * fq;
; #pragma unroll
;         for (int ai = 0; ai < 2; ++ai)
; #pragma unroll
;             for (int m = 0; m < 4; ++m) { const int row = row0 + ai * HALF + m * 16; const size_t off = (size_t)row * ldc + col0;
;                 const float nrl = -1.4426950408889634f * __builtin_amdgcn_rsqf(__hip_atomic_load(rowsq + row, __ATOMIC_RELAXED, __HIP_MEMORY_SCOPE_AGENT) * (1.f / (float)ldc) + eps);
; #pragma unroll
;                 for (int bj = 0; bj < 2; ++bj) { const size_t o2 = off + bj * HALF; const u32x4 xw = *(const u32x4*)(xb + o2), g = *(const u32x4*)(pl + o2);
;                     f32x4 b0, b1, p0, p1;
;                     b0[0] = __uint_as_float(xw.x << 16); b0[1] = __uint_as_float(xw.x & 0xffff0000u); b0[2] = __uint_as_float(xw.y << 16); b0[3] = __uint_as_float(xw.y & 0xffff0000u);
;                     b1[0] = __uint_as_float(xw.z << 16); b1[1] = __uint_as_float(xw.z & 0xffff0000u); b1[2] = __uint_as_float(xw.w << 16); b1[3] = __uint_as_float(xw.w & 0xffff0000u);
;                     p0[0] = __uint_as_float(g.x << 16); p0[1] = __uint_as_float(g.x & 0xffff0000u); p0[2] = __uint_as_float(g.y << 16); p0[3] = __uint_as_float(g.y & 0xffff0000u);
;                     p1[0] = __uint_as_float(g.z << 16); p1[1] = __uint_as_float(g.z & 0xffff0000u); p1[2] = __uint_as_float(g.w << 16); p1[3] = __uint_as_float(g.w & 0xffff0000u);
;                     f32x4 s0, s1;
; #pragma unroll
;                     for (int e = 0; e < 4; ++e) { s0[e] = __builtin_amdgcn_rcpf(1.f + __builtin_amdgcn_exp2f(nrl * acc[ai][bj][m][0][e])); s1[e] = __builtin_amdgcn_rcpf(1.f + __builtin_amdgcn_exp2f(nrl * acc[ai][bj][m][1][e])); }
;                     *(f32x4*)(out + o2) = b0 + s0 * p0; *(f32x4*)(out + o2 + 4) = b1 + s1 * p1; }
;                 if (m & 1) asm volatile("" ::: "memory"); }
.LBB0_727:
	s_lshl_b32 s8, s38, 8
	s_add_i32 s8, s8, s55
	s_lshl_b32 s2, s2, 8
	s_or_b32 s2, s2, s56
	v_add_u32_e32 v144, s8, v148
	v_lshl_add_u32 v145, v149, 3, s2
	v_lshl_add_u32 v146, v144, 10, v145
	v_lshlrev_b32_e32 v156, 2, v144
	v_lshlrev_b32_e32 v147, 1, v146
	v_lshlrev_b32_e32 v155, 2, v146
	s_andn2_b64 vcc, exec, s[0:1]
	s_mov_b64 s[0:1], -1
	s_mov_b64 s[72:73], s[46:47]
	s_mov_b64 s[74:75], s[6:7]
	global_load_dword v198, v156, s[70:71] sc1
	global_load_dwordx4 v[182:185], v147, s[72:73] nt
	global_load_dwordx4 v[190:193], v147, s[74:75] nt
	global_load_dwordx4 v[186:189], v147, s[72:73] offset:256 nt
	global_load_dwordx4 v[194:197], v147, s[74:75] offset:256 nt
	s_add_u32 s72, s46, 0x8000
	s_addc_u32 s73, s47, 0
	s_add_u32 s74, s6, 0x8000
	s_addc_u32 s75, s7, 0
	global_load_dword v216, v156, s[70:71] offset:64 sc1
	global_load_dwordx4 v[200:203], v147, s[72:73] nt
	global_load_dwordx4 v[208:211], v147, s[74:75] nt
	global_load_dwordx4 v[204:207], v147, s[72:73] offset:256 nt
	global_load_dwordx4 v[212:215], v147, s[74:75] offset:256 nt
	s_add_u32 s72, s46, 0x10000
	s_addc_u32 s73, s47, 0
	s_add_u32 s74, s6, 0x10000
	s_addc_u32 s75, s7, 0
	global_load_dword v234, v156, s[70:71] offset:128 sc1
	global_load_dwordx4 v[218:221], v147, s[72:73] nt
	global_load_dwordx4 v[226:229], v147, s[74:75] nt
	global_load_dwordx4 v[222:225], v147, s[72:73] offset:256 nt
	global_load_dwordx4 v[230:233], v147, s[74:75] offset:256 nt
	s_add_u32 s72, s46, 0x18000
	s_addc_u32 s73, s47, 0
	s_add_u32 s74, s6, 0x18000
	s_addc_u32 s75, s7, 0
	global_load_dword v252, v156, s[70:71] offset:192 sc1
	global_load_dwordx4 v[236:239], v147, s[72:73] nt
	global_load_dwordx4 v[244:247], v147, s[74:75] nt
	global_load_dwordx4 v[240:243], v147, s[72:73] offset:256 nt
	global_load_dwordx4 v[248:251], v147, s[74:75] offset:256 nt
	s_waitcnt vmcnt(15)
	v_fmamk_f32 v157, v198, 0x3a800000, v154
	v_rsq_f32_e32 v157, v157
	s_mov_b64 s[76:77], s[80:81]
	s_nop 0
	v_mul_f32_e32 v157, 0xbfb8aa3b, v157
	v_mul_f32_e32 v120, v120, v157
	v_mul_f32_e32 v121, v121, v157
	v_mul_f32_e32 v122, v122, v157
	v_mul_f32_e32 v123, v123, v157
	v_mul_f32_e32 v124, v124, v157
	v_mul_f32_e32 v125, v125, v157
	v_mul_f32_e32 v126, v126, v157
	v_mul_f32_e32 v127, v127, v157
	v_exp_f32_e32 v120, v120
	v_exp_f32_e32 v121, v121
	v_exp_f32_e32 v122, v122
	v_exp_f32_e32 v123, v123
	v_exp_f32_e32 v124, v124
	v_exp_f32_e32 v125, v125
	v_exp_f32_e32 v126, v126
	v_exp_f32_e32 v127, v127
	v_add_f32_e32 v120, 1.0, v120
	v_add_f32_e32 v121, 1.0, v121
	v_add_f32_e32 v122, 1.0, v122
	v_add_f32_e32 v123, 1.0, v123
	v_add_f32_e32 v124, 1.0, v124
	v_add_f32_e32 v125, 1.0, v125
	v_add_f32_e32 v126, 1.0, v126
	v_add_f32_e32 v127, 1.0, v127
	v_rcp_f32_e32 v120, v120
	v_rcp_f32_e32 v121, v121
	v_rcp_f32_e32 v122, v122
	v_rcp_f32_e32 v123, v123
	v_rcp_f32_e32 v124, v124
	v_rcp_f32_e32 v125, v125
	v_rcp_f32_e32 v126, v126
	v_rcp_f32_e32 v127, v127
	v_lshlrev_b32_e32 v158, 16, v182
	v_and_b32_e32 v159, 0xffff0000, v182
	v_lshlrev_b32_e32 v166, 16, v190
	v_and_b32_e32 v167, 0xffff0000, v190
	v_lshlrev_b32_e32 v160, 16, v183
	v_and_b32_e32 v161, 0xffff0000, v183
	v_lshlrev_b32_e32 v168, 16, v191
	v_and_b32_e32 v169, 0xffff0000, v191
	v_lshlrev_b32_e32 v162, 16, v184
	v_and_b32_e32 v163, 0xffff0000, v184
	v_lshlrev_b32_e32 v170, 16, v192
	v_and_b32_e32 v171, 0xffff0000, v192
	v_lshlrev_b32_e32 v164, 16, v185
	v_and_b32_e32 v165, 0xffff0000, v185
	v_lshlrev_b32_e32 v172, 16, v193
	v_and_b32_e32 v173, 0xffff0000, v193
	v_pk_fma_f32 v[124:125], v[124:125], v[166:167], v[158:159]
	v_pk_fma_f32 v[126:127], v[126:127], v[168:169], v[160:161]
	v_pk_fma_f32 v[120:121], v[120:121], v[170:171], v[162:163]
	v_pk_fma_f32 v[122:123], v[122:123], v[172:173], v[164:165]
	global_store_dwordx4 v155, v[124:127], s[76:77] nt
	global_store_dwordx4 v155, v[120:123], s[76:77] offset:16 nt
	v_mul_f32_e32 v112, v112, v157
	v_mul_f32_e32 v113, v113, v157
	v_mul_f32_e32 v114, v114, v157
	v_mul_f32_e32 v115, v115, v157
	v_mul_f32_e32 v116, v116, v157
	v_mul_f32_e32 v117, v117, v157
	v_mul_f32_e32 v118, v118, v157
	v_mul_f32_e32 v119, v119, v157
	v_exp_f32_e32 v112, v112
	v_exp_f32_e32 v113, v113
	v_exp_f32_e32 v114, v114
	v_exp_f32_e32 v115, v115
	v_exp_f32_e32 v116, v116
	v_exp_f32_e32 v117, v117
	v_exp_f32_e32 v118, v118
	v_exp_f32_e32 v119, v119
	v_add_f32_e32 v112, 1.0, v112
	v_add_f32_e32 v113, 1.0, v113
	v_add_f32_e32 v114, 1.0, v114
	v_add_f32_e32 v115, 1.0, v115
	v_add_f32_e32 v116, 1.0, v116
	v_add_f32_e32 v117, 1.0, v117
	v_add_f32_e32 v118, 1.0, v118
	v_add_f32_e32 v119, 1.0, v119
	v_rcp_f32_e32 v112, v112
	v_rcp_f32_e32 v113, v113
	v_rcp_f32_e32 v114, v114
	v_rcp_f32_e32 v115, v115
	v_rcp_f32_e32 v116, v116
	v_rcp_f32_e32 v117, v117
	v_rcp_f32_e32 v118, v118
	v_rcp_f32_e32 v119, v119
	v_lshlrev_b32_e32 v158, 16, v186
	v_and_b32_e32 v159, 0xffff0000, v186
	v_lshlrev_b32_e32 v166, 16, v194
	v_and_b32_e32 v167, 0xffff0000, v194
	v_lshlrev_b32_e32 v160, 16, v187
	v_and_b32_e32 v161, 0xffff0000, v187
	v_lshlrev_b32_e32 v168, 16, v195
	v_and_b32_e32 v169, 0xffff0000, v195
	v_lshlrev_b32_e32 v162, 16, v188
	v_and_b32_e32 v163, 0xffff0000, v188
	v_lshlrev_b32_e32 v170, 16, v196
	v_and_b32_e32 v171, 0xffff0000, v196
	v_lshlrev_b32_e32 v164, 16, v189
	v_and_b32_e32 v165, 0xffff0000, v189
	v_lshlrev_b32_e32 v172, 16, v197
	v_and_b32_e32 v173, 0xffff0000, v197
	v_pk_fma_f32 v[116:117], v[116:117], v[166:167], v[158:159]
	v_pk_fma_f32 v[118:119], v[118:119], v[168:169], v[160:161]
	v_pk_fma_f32 v[112:113], v[112:113], v[170:171], v[162:163]
	v_pk_fma_f32 v[114:115], v[114:115], v[172:173], v[164:165]
	global_store_dwordx4 v155, v[116:119], s[76:77] offset:512 nt
	global_store_dwordx4 v155, v[112:115], s[76:77] offset:528 nt
	s_add_u32 s72, s46, 0x40000
	s_addc_u32 s73, s47, 0
	s_add_u32 s74, s6, 0x40000
	s_addc_u32 s75, s7, 0
	global_load_dword v198, v156, s[70:71] offset:512 sc1
	global_load_dwordx4 v[182:185], v147, s[72:73] nt
	global_load_dwordx4 v[190:193], v147, s[74:75] nt
	global_load_dwordx4 v[186:189], v147, s[72:73] offset:256 nt
	global_load_dwordx4 v[194:197], v147, s[74:75] offset:256 nt
	s_waitcnt vmcnt(19)
;     __device__ __forceinline__ void operator()(const f32x4 (&acc)[2][2][4][2], const Unit& u, int wr, int wc, int fr, int fq) const {
;     ...
;             for (int m = 0; m < 4; ++m) { const int row = row0 + ai * HALF + m * 16; const size_t off = (size_t)row * ldc + col0;
;                 const float nrl = -1.4426950408889634f * __builtin_amdgcn_rsqf(__hip_atomic_load(rowsq + row, __ATOMIC_RELAXED, __HIP_MEMORY_SCOPE_AGENT) * (1.f / (float)ldc) + eps);
; #pragma unroll
;                 for (int bj = 0; bj < 2; ++bj) { const size_t o2 = off + bj * HALF; const u32x4 xw = *(const u32x4*)(xb + o2), g = *(const u32x4*)(pl + o2);
;                     f32x4 b0, b1, p0, p1;
;                     b0[0] = __uint_as_float(xw.x << 16); b0[1] = __uint_as_float(xw.x & 0xffff0000u); b0[2] = __uint_as_float(xw.y << 16); b0[3] = __uint_as_float(xw.y & 0xffff0000u);
;                     b1[0] = __uint_as_float(xw.z << 16); b1[1] = __uint_as_float(xw.z & 0xffff0000u); b1[2] = __uint_as_float(xw.w << 16); b1[3] = __uint_as_float(xw.w & 0xffff0000u);
;                     p0[0] = __uint_as_float(g.x << 16); p0[1] = __uint_as_float(g.x & 0xffff0000u); p0[2] = __uint_as_float(g.y << 16); p0[3] = __uint_as_float(g.y & 0xffff0000u);
;                     p1[0] = __uint_as_float(g.z << 16); p1[1] = __uint_as_float(g.z & 0xffff0000u); p1[2] = __uint_as_float(g.w << 16); p1[3] = __uint_as_float(g.w & 0xffff0000u);
;                     f32x4 s0, s1;
; #pragma unroll
;                     for (int e = 0; e < 4; ++e) { s0[e] = __builtin_amdgcn_rcpf(1.f + __builtin_amdgcn_exp2f(nrl * acc[ai][bj][m][0][e])); s1[e] = __builtin_amdgcn_rcpf(1.f + __builtin_amdgcn_exp2f(nrl * acc[ai][bj][m][1][e])); }
;                     *(f32x4*)(out + o2) = b0 + s0 * p0; *(f32x4*)(out + o2 + 4) = b1 + s1 * p1; }
;                 if (m & 1) asm volatile("" ::: "memory"); }
	v_fmamk_f32 v157, v216, 0x3a800000, v154
	v_rsq_f32_e32 v157, v157
	s_add_u32 s76, s80, 0x10000
	s_addc_u32 s77, s81, 0
	v_mul_f32_e32 v157, 0xbfb8aa3b, v157
	v_mul_f32_e32 v104, v104, v157
	v_mul_f32_e32 v105, v105, v157
	v_mul_f32_e32 v106, v106, v157
	v_mul_f32_e32 v107, v107, v157
	v_mul_f32_e32 v108, v108, v157
	v_mul_f32_e32 v109, v109, v157
	v_mul_f32_e32 v110, v110, v157
	v_mul_f32_e32 v111, v111, v157
	v_exp_f32_e32 v104, v104
	v_exp_f32_e32 v105, v105
	v_exp_f32_e32 v106, v106
	v_exp_f32_e32 v107, v107
	v_exp_f32_e32 v108, v108
	v_exp_f32_e32 v109, v109
	v_exp_f32_e32 v110, v110
	v_exp_f32_e32 v111, v111
	v_add_f32_e32 v104, 1.0, v104
	v_add_f32_e32 v105, 1.0, v105
	v_add_f32_e32 v106, 1.0, v106
	v_add_f32_e32 v107, 1.0, v107
	v_add_f32_e32 v108, 1.0, v108
	v_add_f32_e32 v109, 1.0, v109
	v_add_f32_e32 v110, 1.0, v110
	v_add_f32_e32 v111, 1.0, v111
	v_rcp_f32_e32 v104, v104
	v_rcp_f32_e32 v105, v105
	v_rcp_f32_e32 v106, v106
	v_rcp_f32_e32 v107, v107
	v_rcp_f32_e32 v108, v108
	v_rcp_f32_e32 v109, v109
	v_rcp_f32_e32 v110, v110
	v_rcp_f32_e32 v111, v111
	v_lshlrev_b32_e32 v158, 16, v200
	v_and_b32_e32 v159, 0xffff0000, v200
	v_lshlrev_b32_e32 v166, 16, v208
	v_and_b32_e32 v167, 0xffff0000, v208
	v_lshlrev_b32_e32 v160, 16, v201
	v_and_b32_e32 v161, 0xffff0000, v201
	v_lshlrev_b32_e32 v168, 16, v209
	v_and_b32_e32 v169, 0xffff0000, v209
	v_lshlrev_b32_e32 v162, 16, v202
	v_and_b32_e32 v163, 0xffff0000, v202
	v_lshlrev_b32_e32 v170, 16, v210
	v_and_b32_e32 v171, 0xffff0000, v210
	v_lshlrev_b32_e32 v164, 16, v203
	v_and_b32_e32 v165, 0xffff0000, v203
	v_lshlrev_b32_e32 v172, 16, v211
	v_and_b32_e32 v173, 0xffff0000, v211
	v_pk_fma_f32 v[108:109], v[108:109], v[166:167], v[158:159]
	v_pk_fma_f32 v[110:111], v[110:111], v[168:169], v[160:161]
	v_pk_fma_f32 v[104:105], v[104:105], v[170:171], v[162:163]
	v_pk_fma_f32 v[106:107], v[106:107], v[172:173], v[164:165]
	global_store_dwordx4 v155, v[108:111], s[76:77] nt
	global_store_dwordx4 v155, v[104:107], s[76:77] offset:16 nt
	v_mul_f32_e32 v96, v96, v157
	v_mul_f32_e32 v97, v97, v157
	v_mul_f32_e32 v98, v98, v157
	v_mul_f32_e32 v99, v99, v157
	v_mul_f32_e32 v100, v100, v157
	v_mul_f32_e32 v101, v101, v157
	v_mul_f32_e32 v102, v102, v157
	v_mul_f32_e32 v103, v103, v157
	v_exp_f32_e32 v96, v96
	v_exp_f32_e32 v97, v97
	v_exp_f32_e32 v98, v98
	v_exp_f32_e32 v99, v99
	v_exp_f32_e32 v100, v100
	v_exp_f32_e32 v101, v101
	v_exp_f32_e32 v102, v102
	v_exp_f32_e32 v103, v103
	v_add_f32_e32 v96, 1.0, v96
	v_add_f32_e32 v97, 1.0, v97
	v_add_f32_e32 v98, 1.0, v98
	v_add_f32_e32 v99, 1.0, v99
	v_add_f32_e32 v100, 1.0, v100
	v_add_f32_e32 v101, 1.0, v101
	v_add_f32_e32 v102, 1.0, v102
	v_add_f32_e32 v103, 1.0, v103
	v_rcp_f32_e32 v96, v96
	v_rcp_f32_e32 v97, v97
	v_rcp_f32_e32 v98, v98
	v_rcp_f32_e32 v99, v99
	v_rcp_f32_e32 v100, v100
	v_rcp_f32_e32 v101, v101
	v_rcp_f32_e32 v102, v102
	v_rcp_f32_e32 v103, v103
	v_lshlrev_b32_e32 v158, 16, v204
	v_and_b32_e32 v159, 0xffff0000, v204
	v_lshlrev_b32_e32 v166, 16, v212
	v_and_b32_e32 v167, 0xffff0000, v212
	v_lshlrev_b32_e32 v160, 16, v205
	v_and_b32_e32 v161, 0xffff0000, v205
	v_lshlrev_b32_e32 v168, 16, v213
	v_and_b32_e32 v169, 0xffff0000, v213
	v_lshlrev_b32_e32 v162, 16, v206
	v_and_b32_e32 v163, 0xffff0000, v206
	v_lshlrev_b32_e32 v170, 16, v214
	v_and_b32_e32 v171, 0xffff0000, v214
	v_lshlrev_b32_e32 v164, 16, v207
	v_and_b32_e32 v165, 0xffff0000, v207
	v_lshlrev_b32_e32 v172, 16, v215
	v_and_b32_e32 v173, 0xffff0000, v215
	v_pk_fma_f32 v[100:101], v[100:101], v[166:167], v[158:159]
	v_pk_fma_f32 v[102:103], v[102:103], v[168:169], v[160:161]
	v_pk_fma_f32 v[96:97], v[96:97], v[170:171], v[162:163]
	v_pk_fma_f32 v[98:99], v[98:99], v[172:173], v[164:165]
	global_store_dwordx4 v155, v[100:103], s[76:77] offset:512 nt
	global_store_dwordx4 v155, v[96:99], s[76:77] offset:528 nt
	s_add_u32 s72, s46, 0x48000
	s_addc_u32 s73, s47, 0
	s_add_u32 s74, s6, 0x48000
	s_addc_u32 s75, s7, 0
	global_load_dword v216, v156, s[70:71] offset:576 sc1
	global_load_dwordx4 v[200:203], v147, s[72:73] nt
	global_load_dwordx4 v[208:211], v147, s[74:75] nt
	global_load_dwordx4 v[204:207], v147, s[72:73] offset:256 nt
	global_load_dwordx4 v[212:215], v147, s[74:75] offset:256 nt
	s_waitcnt vmcnt(23)
;     __device__ __forceinline__ void operator()(const f32x4 (&acc)[2][2][4][2], const Unit& u, int wr, int wc, int fr, int fq) const {
;     ...
;             for (int m = 0; m < 4; ++m) { const int row = row0 + ai * HALF + m * 16; const size_t off = (size_t)row * ldc + col0;
;                 const float nrl = -1.4426950408889634f * __builtin_amdgcn_rsqf(__hip_atomic_load(rowsq + row, __ATOMIC_RELAXED, __HIP_MEMORY_SCOPE_AGENT) * (1.f / (float)ldc) + eps);
; #pragma unroll
;                 for (int bj = 0; bj < 2; ++bj) { const size_t o2 = off + bj * HALF; const u32x4 xw = *(const u32x4*)(xb + o2), g = *(const u32x4*)(pl + o2);
;                     f32x4 b0, b1, p0, p1;
;                     b0[0] = __uint_as_float(xw.x << 16); b0[1] = __uint_as_float(xw.x & 0xffff0000u); b0[2] = __uint_as_float(xw.y << 16); b0[3] = __uint_as_float(xw.y & 0xffff0000u);
;                     b1[0] = __uint_as_float(xw.z << 16); b1[1] = __uint_as_float(xw.z & 0xffff0000u); b1[2] = __uint_as_float(xw.w << 16); b1[3] = __uint_as_float(xw.w & 0xffff0000u);
;                     p0[0] = __uint_as_float(g.x << 16); p0[1] = __uint_as_float(g.x & 0xffff0000u); p0[2] = __uint_as_float(g.y << 16); p0[3] = __uint_as_float(g.y & 0xffff0000u);
;                     p1[0] = __uint_as_float(g.z << 16); p1[1] = __uint_as_float(g.z & 0xffff0000u); p1[2] = __uint_as_float(g.w << 16); p1[3] = __uint_as_float(g.w & 0xffff0000u);
;                     f32x4 s0, s1;
; #pragma unroll
;                     for (int e = 0; e < 4; ++e) { s0[e] = __builtin_amdgcn_rcpf(1.f + __builtin_amdgcn_exp2f(nrl * acc[ai][bj][m][0][e])); s1[e] = __builtin_amdgcn_rcpf(1.f + __builtin_amdgcn_exp2f(nrl * acc[ai][bj][m][1][e])); }
;                     *(f32x4*)(out + o2) = b0 + s0 * p0; *(f32x4*)(out + o2 + 4) = b1 + s1 * p1; }
;                 if (m & 1) asm volatile("" ::: "memory"); }
	v_fmamk_f32 v157, v234, 0x3a800000, v154
	v_rsq_f32_e32 v157, v157
	s_add_u32 s76, s80, 0x20000
	s_addc_u32 s77, s81, 0
	v_mul_f32_e32 v157, 0xbfb8aa3b, v157
	v_mul_f32_e32 v88, v88, v157
	v_mul_f32_e32 v89, v89, v157
	v_mul_f32_e32 v90, v90, v157
	v_mul_f32_e32 v91, v91, v157
	v_mul_f32_e32 v92, v92, v157
	v_mul_f32_e32 v93, v93, v157
	v_mul_f32_e32 v94, v94, v157
	v_mul_f32_e32 v95, v95, v157
	v_exp_f32_e32 v88, v88
	v_exp_f32_e32 v89, v89
	v_exp_f32_e32 v90, v90
	v_exp_f32_e32 v91, v91
	v_exp_f32_e32 v92, v92
	v_exp_f32_e32 v93, v93
	v_exp_f32_e32 v94, v94
	v_exp_f32_e32 v95, v95
	v_add_f32_e32 v88, 1.0, v88
	v_add_f32_e32 v89, 1.0, v89
	v_add_f32_e32 v90, 1.0, v90
	v_add_f32_e32 v91, 1.0, v91
	v_add_f32_e32 v92, 1.0, v92
	v_add_f32_e32 v93, 1.0, v93
	v_add_f32_e32 v94, 1.0, v94
	v_add_f32_e32 v95, 1.0, v95
	v_rcp_f32_e32 v88, v88
	v_rcp_f32_e32 v89, v89
	v_rcp_f32_e32 v90, v90
	v_rcp_f32_e32 v91, v91
	v_rcp_f32_e32 v92, v92
	v_rcp_f32_e32 v93, v93
	v_rcp_f32_e32 v94, v94
	v_rcp_f32_e32 v95, v95
	v_lshlrev_b32_e32 v158, 16, v218
	v_and_b32_e32 v159, 0xffff0000, v218
	v_lshlrev_b32_e32 v166, 16, v226
	v_and_b32_e32 v167, 0xffff0000, v226
	v_lshlrev_b32_e32 v160, 16, v219
	v_and_b32_e32 v161, 0xffff0000, v219
	v_lshlrev_b32_e32 v168, 16, v227
	v_and_b32_e32 v169, 0xffff0000, v227
	v_lshlrev_b32_e32 v162, 16, v220
	v_and_b32_e32 v163, 0xffff0000, v220
	v_lshlrev_b32_e32 v170, 16, v228
	v_and_b32_e32 v171, 0xffff0000, v228
	v_lshlrev_b32_e32 v164, 16, v221
	v_and_b32_e32 v165, 0xffff0000, v221
	v_lshlrev_b32_e32 v172, 16, v229
	v_and_b32_e32 v173, 0xffff0000, v229
	v_pk_fma_f32 v[92:93], v[92:93], v[166:167], v[158:159]
	v_pk_fma_f32 v[94:95], v[94:95], v[168:169], v[160:161]
	v_pk_fma_f32 v[88:89], v[88:89], v[170:171], v[162:163]
	v_pk_fma_f32 v[90:91], v[90:91], v[172:173], v[164:165]
	global_store_dwordx4 v155, v[92:95], s[76:77] nt
	global_store_dwordx4 v155, v[88:91], s[76:77] offset:16 nt
	v_mul_f32_e32 v80, v80, v157
	v_mul_f32_e32 v81, v81, v157
	v_mul_f32_e32 v82, v82, v157
	v_mul_f32_e32 v83, v83, v157
	v_mul_f32_e32 v84, v84, v157
	v_mul_f32_e32 v85, v85, v157
	v_mul_f32_e32 v86, v86, v157
	v_mul_f32_e32 v87, v87, v157
	v_exp_f32_e32 v80, v80
	v_exp_f32_e32 v81, v81
	v_exp_f32_e32 v82, v82
	v_exp_f32_e32 v83, v83
	v_exp_f32_e32 v84, v84
	v_exp_f32_e32 v85, v85
	v_exp_f32_e32 v86, v86
	v_exp_f32_e32 v87, v87
	v_add_f32_e32 v80, 1.0, v80
	v_add_f32_e32 v81, 1.0, v81
	v_add_f32_e32 v82, 1.0, v82
	v_add_f32_e32 v83, 1.0, v83
	v_add_f32_e32 v84, 1.0, v84
	v_add_f32_e32 v85, 1.0, v85
	v_add_f32_e32 v86, 1.0, v86
	v_add_f32_e32 v87, 1.0, v87
	v_rcp_f32_e32 v80, v80
	v_rcp_f32_e32 v81, v81
	v_rcp_f32_e32 v82, v82
	v_rcp_f32_e32 v83, v83
	v_rcp_f32_e32 v84, v84
	v_rcp_f32_e32 v85, v85
	v_rcp_f32_e32 v86, v86
	v_rcp_f32_e32 v87, v87
	v_lshlrev_b32_e32 v158, 16, v222
	v_and_b32_e32 v159, 0xffff0000, v222
	v_lshlrev_b32_e32 v166, 16, v230
	v_and_b32_e32 v167, 0xffff0000, v230
	v_lshlrev_b32_e32 v160, 16, v223
	v_and_b32_e32 v161, 0xffff0000, v223
	v_lshlrev_b32_e32 v168, 16, v231
	v_and_b32_e32 v169, 0xffff0000, v231
	v_lshlrev_b32_e32 v162, 16, v224
	v_and_b32_e32 v163, 0xffff0000, v224
	v_lshlrev_b32_e32 v170, 16, v232
	v_and_b32_e32 v171, 0xffff0000, v232
	v_lshlrev_b32_e32 v164, 16, v225
	v_and_b32_e32 v165, 0xffff0000, v225
	v_lshlrev_b32_e32 v172, 16, v233
	v_and_b32_e32 v173, 0xffff0000, v233
	v_pk_fma_f32 v[84:85], v[84:85], v[166:167], v[158:159]
	v_pk_fma_f32 v[86:87], v[86:87], v[168:169], v[160:161]
	v_pk_fma_f32 v[80:81], v[80:81], v[170:171], v[162:163]
	v_pk_fma_f32 v[82:83], v[82:83], v[172:173], v[164:165]
	global_store_dwordx4 v155, v[84:87], s[76:77] offset:512 nt
	global_store_dwordx4 v155, v[80:83], s[76:77] offset:528 nt
	s_add_u32 s72, s46, 0x50000
	s_addc_u32 s73, s47, 0
	s_add_u32 s74, s6, 0x50000
	s_addc_u32 s75, s7, 0
	global_load_dword v234, v156, s[70:71] offset:640 sc1
	global_load_dwordx4 v[218:221], v147, s[72:73] nt
	global_load_dwordx4 v[226:229], v147, s[74:75] nt
	global_load_dwordx4 v[222:225], v147, s[72:73] offset:256 nt
	global_load_dwordx4 v[230:233], v147, s[74:75] offset:256 nt
	s_waitcnt vmcnt(27)
	v_fmamk_f32 v157, v252, 0x3a800000, v154
	v_rsq_f32_e32 v157, v157
	s_add_u32 s76, s80, 0x30000
	s_addc_u32 s77, s81, 0
	v_mul_f32_e32 v157, 0xbfb8aa3b, v157
	v_mul_f32_e32 v72, v72, v157
	v_mul_f32_e32 v73, v73, v157
	v_mul_f32_e32 v74, v74, v157
	v_mul_f32_e32 v75, v75, v157
	v_mul_f32_e32 v76, v76, v157
	v_mul_f32_e32 v77, v77, v157
	v_mul_f32_e32 v78, v78, v157
	v_mul_f32_e32 v79, v79, v157
	v_exp_f32_e32 v72, v72
	v_exp_f32_e32 v73, v73
	v_exp_f32_e32 v74, v74
	v_exp_f32_e32 v75, v75
	v_exp_f32_e32 v76, v76
	v_exp_f32_e32 v77, v77
	v_exp_f32_e32 v78, v78
	v_exp_f32_e32 v79, v79
	v_add_f32_e32 v72, 1.0, v72
	v_add_f32_e32 v73, 1.0, v73
	v_add_f32_e32 v74, 1.0, v74
	v_add_f32_e32 v75, 1.0, v75
	v_add_f32_e32 v76, 1.0, v76
	v_add_f32_e32 v77, 1.0, v77
	v_add_f32_e32 v78, 1.0, v78
	v_add_f32_e32 v79, 1.0, v79
	v_rcp_f32_e32 v72, v72
	v_rcp_f32_e32 v73, v73
	v_rcp_f32_e32 v74, v74
	v_rcp_f32_e32 v75, v75
	v_rcp_f32_e32 v76, v76
	v_rcp_f32_e32 v77, v77
	v_rcp_f32_e32 v78, v78
	v_rcp_f32_e32 v79, v79
	v_lshlrev_b32_e32 v158, 16, v236
	v_and_b32_e32 v159, 0xffff0000, v236
	v_lshlrev_b32_e32 v166, 16, v244
	v_and_b32_e32 v167, 0xffff0000, v244
	v_lshlrev_b32_e32 v160, 16, v237
	v_and_b32_e32 v161, 0xffff0000, v237
	v_lshlrev_b32_e32 v168, 16, v245
	v_and_b32_e32 v169, 0xffff0000, v245
	v_lshlrev_b32_e32 v162, 16, v238
	v_and_b32_e32 v163, 0xffff0000, v238
	v_lshlrev_b32_e32 v170, 16, v246
	v_and_b32_e32 v171, 0xffff0000, v246
	v_lshlrev_b32_e32 v164, 16, v239
	v_and_b32_e32 v165, 0xffff0000, v239
;     __device__ __forceinline__ void operator()(const f32x4 (&acc)[2][2][4][2], const Unit& u, int wr, int wc, int fr, int fq) const {
;     ...
;             for (int m = 0; m < 4; ++m) { const int row = row0 + ai * HALF + m * 16; const size_t off = (size_t)row * ldc + col0;
;                 const float nrl = -1.4426950408889634f * __builtin_amdgcn_rsqf(__hip_atomic_load(rowsq + row, __ATOMIC_RELAXED, __HIP_MEMORY_SCOPE_AGENT) * (1.f / (float)ldc) + eps);
; #pragma unroll
;                 for (int bj = 0; bj < 2; ++bj) { const size_t o2 = off + bj * HALF; const u32x4 xw = *(const u32x4*)(xb + o2), g = *(const u32x4*)(pl + o2);
;                     f32x4 b0, b1, p0, p1;
;                     b0[0] = __uint_as_float(xw.x << 16); b0[1] = __uint_as_float(xw.x & 0xffff0000u); b0[2] = __uint_as_float(xw.y << 16); b0[3] = __uint_as_float(xw.y & 0xffff0000u);
;                     b1[0] = __uint_as_float(xw.z << 16); b1[1] = __uint_as_float(xw.z & 0xffff0000u); b1[2] = __uint_as_float(xw.w << 16); b1[3] = __uint_as_float(xw.w & 0xffff0000u);
;                     p0[0] = __uint_as_float(g.x << 16); p0[1] = __uint_as_float(g.x & 0xffff0000u); p0[2] = __uint_as_float(g.y << 16); p0[3] = __uint_as_float(g.y & 0xffff0000u);
;                     p1[0] = __uint_as_float(g.z << 16); p1[1] = __uint_as_float(g.z & 0xffff0000u); p1[2] = __uint_as_float(g.w << 16); p1[3] = __uint_as_float(g.w & 0xffff0000u);
;                     f32x4 s0, s1;
; #pragma unroll
;                     for (int e = 0; e < 4; ++e) { s0[e] = __builtin_amdgcn_rcpf(1.f + __builtin_amdgcn_exp2f(nrl * acc[ai][bj][m][0][e])); s1[e] = __builtin_amdgcn_rcpf(1.f + __builtin_amdgcn_exp2f(nrl * acc[ai][bj][m][1][e])); }
;                     *(f32x4*)(out + o2) = b0 + s0 * p0; *(f32x4*)(out + o2 + 4) = b1 + s1 * p1; }
;                 if (m & 1) asm volatile("" ::: "memory"); }
	v_lshlrev_b32_e32 v172, 16, v247
	v_and_b32_e32 v173, 0xffff0000, v247
	v_pk_fma_f32 v[76:77], v[76:77], v[166:167], v[158:159]
	v_pk_fma_f32 v[78:79], v[78:79], v[168:169], v[160:161]
	v_pk_fma_f32 v[72:73], v[72:73], v[170:171], v[162:163]
	v_pk_fma_f32 v[74:75], v[74:75], v[172:173], v[164:165]
	global_store_dwordx4 v155, v[76:79], s[76:77] nt
	global_store_dwordx4 v155, v[72:75], s[76:77] offset:16 nt
	v_mul_f32_e32 v64, v64, v157
	v_mul_f32_e32 v65, v65, v157
	v_mul_f32_e32 v66, v66, v157
	v_mul_f32_e32 v67, v67, v157
	v_mul_f32_e32 v68, v68, v157
	v_mul_f32_e32 v69, v69, v157
	v_mul_f32_e32 v70, v70, v157
	v_mul_f32_e32 v71, v71, v157
	v_exp_f32_e32 v64, v64
	v_exp_f32_e32 v65, v65
	v_exp_f32_e32 v66, v66
	v_exp_f32_e32 v67, v67
	v_exp_f32_e32 v68, v68
	v_exp_f32_e32 v69, v69
	v_exp_f32_e32 v70, v70
	v_exp_f32_e32 v71, v71
	v_add_f32_e32 v64, 1.0, v64
	v_add_f32_e32 v65, 1.0, v65
	v_add_f32_e32 v66, 1.0, v66
	v_add_f32_e32 v67, 1.0, v67
	v_add_f32_e32 v68, 1.0, v68
	v_add_f32_e32 v69, 1.0, v69
	v_add_f32_e32 v70, 1.0, v70
	v_add_f32_e32 v71, 1.0, v71
	v_rcp_f32_e32 v64, v64
	v_rcp_f32_e32 v65, v65
	v_rcp_f32_e32 v66, v66
	v_rcp_f32_e32 v67, v67
	v_rcp_f32_e32 v68, v68
	v_rcp_f32_e32 v69, v69
	v_rcp_f32_e32 v70, v70
	v_rcp_f32_e32 v71, v71
	v_lshlrev_b32_e32 v158, 16, v240
	v_and_b32_e32 v159, 0xffff0000, v240
	v_lshlrev_b32_e32 v166, 16, v248
	v_and_b32_e32 v167, 0xffff0000, v248
	v_lshlrev_b32_e32 v160, 16, v241
	v_and_b32_e32 v161, 0xffff0000, v241
	v_lshlrev_b32_e32 v168, 16, v249
	v_and_b32_e32 v169, 0xffff0000, v249
	v_lshlrev_b32_e32 v162, 16, v242
	v_and_b32_e32 v163, 0xffff0000, v242
	v_lshlrev_b32_e32 v170, 16, v250
	v_and_b32_e32 v171, 0xffff0000, v250
	v_lshlrev_b32_e32 v164, 16, v243
	v_and_b32_e32 v165, 0xffff0000, v243
	v_lshlrev_b32_e32 v172, 16, v251
	v_and_b32_e32 v173, 0xffff0000, v251
	v_pk_fma_f32 v[68:69], v[68:69], v[166:167], v[158:159]
	v_pk_fma_f32 v[70:71], v[70:71], v[168:169], v[160:161]
	v_pk_fma_f32 v[64:65], v[64:65], v[170:171], v[162:163]
	v_pk_fma_f32 v[66:67], v[66:67], v[172:173], v[164:165]
	global_store_dwordx4 v155, v[68:71], s[76:77] offset:512 nt
	global_store_dwordx4 v155, v[64:67], s[76:77] offset:528 nt
	s_add_u32 s72, s46, 0x58000
	s_addc_u32 s73, s47, 0
	s_add_u32 s74, s6, 0x58000
	s_addc_u32 s75, s7, 0
	global_load_dword v252, v156, s[70:71] offset:704 sc1
	global_load_dwordx4 v[236:239], v147, s[72:73] nt
	global_load_dwordx4 v[244:247], v147, s[74:75] nt
	global_load_dwordx4 v[240:243], v147, s[72:73] offset:256 nt
	global_load_dwordx4 v[248:251], v147, s[74:75] offset:256 nt
	s_waitcnt vmcnt(27)
	v_fmamk_f32 v157, v198, 0x3a800000, v154
	v_rsq_f32_e32 v157, v157
	s_add_u32 s76, s80, 0x80000
	s_addc_u32 s77, s81, 0
	v_mul_f32_e32 v157, 0xbfb8aa3b, v157
	v_mul_f32_e32 v56, v56, v157
	v_mul_f32_e32 v57, v57, v157
	v_mul_f32_e32 v58, v58, v157
	v_mul_f32_e32 v59, v59, v157
	v_mul_f32_e32 v60, v60, v157
	v_mul_f32_e32 v61, v61, v157
	v_mul_f32_e32 v62, v62, v157
	v_mul_f32_e32 v63, v63, v157
	v_exp_f32_e32 v56, v56
	v_exp_f32_e32 v57, v57
	v_exp_f32_e32 v58, v58
	v_exp_f32_e32 v59, v59
	v_exp_f32_e32 v60, v60
	v_exp_f32_e32 v61, v61
	v_exp_f32_e32 v62, v62
	v_exp_f32_e32 v63, v63
	v_add_f32_e32 v56, 1.0, v56
	v_add_f32_e32 v57, 1.0, v57
	v_add_f32_e32 v58, 1.0, v58
	v_add_f32_e32 v59, 1.0, v59
	v_add_f32_e32 v60, 1.0, v60
	v_add_f32_e32 v61, 1.0, v61
	v_add_f32_e32 v62, 1.0, v62
	v_add_f32_e32 v63, 1.0, v63
	v_rcp_f32_e32 v56, v56
	v_rcp_f32_e32 v57, v57
	v_rcp_f32_e32 v58, v58
	v_rcp_f32_e32 v59, v59
	v_rcp_f32_e32 v60, v60
	v_rcp_f32_e32 v61, v61
	v_rcp_f32_e32 v62, v62
	v_rcp_f32_e32 v63, v63
	v_lshlrev_b32_e32 v158, 16, v182
	v_and_b32_e32 v159, 0xffff0000, v182
	v_lshlrev_b32_e32 v166, 16, v190
	v_and_b32_e32 v167, 0xffff0000, v190
	v_lshlrev_b32_e32 v160, 16, v183
	v_and_b32_e32 v161, 0xffff0000, v183
	v_lshlrev_b32_e32 v168, 16, v191
	v_and_b32_e32 v169, 0xffff0000, v191
	v_lshlrev_b32_e32 v162, 16, v184
	v_and_b32_e32 v163, 0xffff0000, v184
	v_lshlrev_b32_e32 v170, 16, v192
	v_and_b32_e32 v171, 0xffff0000, v192
	v_lshlrev_b32_e32 v164, 16, v185
	v_and_b32_e32 v165, 0xffff0000, v185
	v_lshlrev_b32_e32 v172, 16, v193
	v_and_b32_e32 v173, 0xffff0000, v193
	v_pk_fma_f32 v[60:61], v[60:61], v[166:167], v[158:159]
	v_pk_fma_f32 v[62:63], v[62:63], v[168:169], v[160:161]
	v_pk_fma_f32 v[56:57], v[56:57], v[170:171], v[162:163]
	v_pk_fma_f32 v[58:59], v[58:59], v[172:173], v[164:165]
	global_store_dwordx4 v155, v[60:63], s[76:77] nt
	global_store_dwordx4 v155, v[56:59], s[76:77] offset:16 nt
	v_mul_f32_e32 v48, v48, v157
	v_mul_f32_e32 v49, v49, v157
	v_mul_f32_e32 v50, v50, v157
	v_mul_f32_e32 v51, v51, v157
	v_mul_f32_e32 v52, v52, v157
	v_mul_f32_e32 v53, v53, v157
	v_mul_f32_e32 v54, v54, v157
	v_mul_f32_e32 v55, v55, v157
	v_exp_f32_e32 v48, v48
	v_exp_f32_e32 v49, v49
	v_exp_f32_e32 v50, v50
	v_exp_f32_e32 v51, v51
	v_exp_f32_e32 v52, v52
	v_exp_f32_e32 v53, v53
	v_exp_f32_e32 v54, v54
	v_exp_f32_e32 v55, v55
	v_add_f32_e32 v48, 1.0, v48
	v_add_f32_e32 v49, 1.0, v49
	v_add_f32_e32 v50, 1.0, v50
	v_add_f32_e32 v51, 1.0, v51
	v_add_f32_e32 v52, 1.0, v52
	v_add_f32_e32 v53, 1.0, v53
	v_add_f32_e32 v54, 1.0, v54
	v_add_f32_e32 v55, 1.0, v55
	v_rcp_f32_e32 v48, v48
	v_rcp_f32_e32 v49, v49
	v_rcp_f32_e32 v50, v50
	v_rcp_f32_e32 v51, v51
	v_rcp_f32_e32 v52, v52
	v_rcp_f32_e32 v53, v53
	v_rcp_f32_e32 v54, v54
	v_rcp_f32_e32 v55, v55
	v_lshlrev_b32_e32 v158, 16, v186
	v_and_b32_e32 v159, 0xffff0000, v186
	v_lshlrev_b32_e32 v166, 16, v194
	v_and_b32_e32 v167, 0xffff0000, v194
	v_lshlrev_b32_e32 v160, 16, v187
	v_and_b32_e32 v161, 0xffff0000, v187
	v_lshlrev_b32_e32 v168, 16, v195
	v_and_b32_e32 v169, 0xffff0000, v195
	v_lshlrev_b32_e32 v162, 16, v188
	v_and_b32_e32 v163, 0xffff0000, v188
	v_lshlrev_b32_e32 v170, 16, v196
	v_and_b32_e32 v171, 0xffff0000, v196
	v_lshlrev_b32_e32 v164, 16, v189
	v_and_b32_e32 v165, 0xffff0000, v189
	v_lshlrev_b32_e32 v172, 16, v197
	v_and_b32_e32 v173, 0xffff0000, v197
	v_pk_fma_f32 v[52:53], v[52:53], v[166:167], v[158:159]
	v_pk_fma_f32 v[54:55], v[54:55], v[168:169], v[160:161]
	v_pk_fma_f32 v[48:49], v[48:49], v[170:171], v[162:163]
	v_pk_fma_f32 v[50:51], v[50:51], v[172:173], v[164:165]
	global_store_dwordx4 v155, v[52:55], s[76:77] offset:512 nt
	global_store_dwordx4 v155, v[48:51], s[76:77] offset:528 nt
	s_waitcnt vmcnt(22)
;     __device__ __forceinline__ void operator()(const f32x4 (&acc)[2][2][4][2], const Unit& u, int wr, int wc, int fr, int fq) const {
;     ...
;             for (int m = 0; m < 4; ++m) { const int row = row0 + ai * HALF + m * 16; const size_t off = (size_t)row * ldc + col0;
;                 const float nrl = -1.4426950408889634f * __builtin_amdgcn_rsqf(__hip_atomic_load(rowsq + row, __ATOMIC_RELAXED, __HIP_MEMORY_SCOPE_AGENT) * (1.f / (float)ldc) + eps);
; #pragma unroll
;                 for (int bj = 0; bj < 2; ++bj) { const size_t o2 = off + bj * HALF; const u32x4 xw = *(const u32x4*)(xb + o2), g = *(const u32x4*)(pl + o2);
;                     f32x4 b0, b1, p0, p1;
;                     b0[0] = __uint_as_float(xw.x << 16); b0[1] = __uint_as_float(xw.x & 0xffff0000u); b0[2] = __uint_as_float(xw.y << 16); b0[3] = __uint_as_float(xw.y & 0xffff0000u);
;                     b1[0] = __uint_as_float(xw.z << 16); b1[1] = __uint_as_float(xw.z & 0xffff0000u); b1[2] = __uint_as_float(xw.w << 16); b1[3] = __uint_as_float(xw.w & 0xffff0000u);
;                     p0[0] = __uint_as_float(g.x << 16); p0[1] = __uint_as_float(g.x & 0xffff0000u); p0[2] = __uint_as_float(g.y << 16); p0[3] = __uint_as_float(g.y & 0xffff0000u);
;                     p1[0] = __uint_as_float(g.z << 16); p1[1] = __uint_as_float(g.z & 0xffff0000u); p1[2] = __uint_as_float(g.w << 16); p1[3] = __uint_as_float(g.w & 0xffff0000u);
;                     f32x4 s0, s1;
; #pragma unroll
;                     for (int e = 0; e < 4; ++e) { s0[e] = __builtin_amdgcn_rcpf(1.f + __builtin_amdgcn_exp2f(nrl * acc[ai][bj][m][0][e])); s1[e] = __builtin_amdgcn_rcpf(1.f + __builtin_amdgcn_exp2f(nrl * acc[ai][bj][m][1][e])); }
;                     *(f32x4*)(out + o2) = b0 + s0 * p0; *(f32x4*)(out + o2 + 4) = b1 + s1 * p1; }
;                 if (m & 1) asm volatile("" ::: "memory"); }
	v_fmamk_f32 v157, v216, 0x3a800000, v154
	v_rsq_f32_e32 v157, v157
	s_add_u32 s76, s80, 0x90000
	s_addc_u32 s77, s81, 0
	v_mul_f32_e32 v157, 0xbfb8aa3b, v157
	v_mul_f32_e32 v40, v40, v157
	v_mul_f32_e32 v41, v41, v157
	v_mul_f32_e32 v42, v42, v157
	v_mul_f32_e32 v43, v43, v157
	v_mul_f32_e32 v44, v44, v157
	v_mul_f32_e32 v45, v45, v157
	v_mul_f32_e32 v46, v46, v157
	v_mul_f32_e32 v47, v47, v157
	v_exp_f32_e32 v40, v40
	v_exp_f32_e32 v41, v41
	v_exp_f32_e32 v42, v42
	v_exp_f32_e32 v43, v43
	v_exp_f32_e32 v44, v44
	v_exp_f32_e32 v45, v45
	v_exp_f32_e32 v46, v46
	v_exp_f32_e32 v47, v47
	v_add_f32_e32 v40, 1.0, v40
	v_add_f32_e32 v41, 1.0, v41
	v_add_f32_e32 v42, 1.0, v42
	v_add_f32_e32 v43, 1.0, v43
	v_add_f32_e32 v44, 1.0, v44
	v_add_f32_e32 v45, 1.0, v45
	v_add_f32_e32 v46, 1.0, v46
	v_add_f32_e32 v47, 1.0, v47
	v_rcp_f32_e32 v40, v40
	v_rcp_f32_e32 v41, v41
	v_rcp_f32_e32 v42, v42
	v_rcp_f32_e32 v43, v43
	v_rcp_f32_e32 v44, v44
	v_rcp_f32_e32 v45, v45
	v_rcp_f32_e32 v46, v46
	v_rcp_f32_e32 v47, v47
	v_lshlrev_b32_e32 v158, 16, v200
	v_and_b32_e32 v159, 0xffff0000, v200
	v_lshlrev_b32_e32 v166, 16, v208
	v_and_b32_e32 v167, 0xffff0000, v208
	v_lshlrev_b32_e32 v160, 16, v201
	v_and_b32_e32 v161, 0xffff0000, v201
	v_lshlrev_b32_e32 v168, 16, v209
	v_and_b32_e32 v169, 0xffff0000, v209
	v_lshlrev_b32_e32 v162, 16, v202
	v_and_b32_e32 v163, 0xffff0000, v202
	v_lshlrev_b32_e32 v170, 16, v210
	v_and_b32_e32 v171, 0xffff0000, v210
	v_lshlrev_b32_e32 v164, 16, v203
	v_and_b32_e32 v165, 0xffff0000, v203
	v_lshlrev_b32_e32 v172, 16, v211
	v_and_b32_e32 v173, 0xffff0000, v211
	v_pk_fma_f32 v[44:45], v[44:45], v[166:167], v[158:159]
	v_pk_fma_f32 v[46:47], v[46:47], v[168:169], v[160:161]
	v_pk_fma_f32 v[40:41], v[40:41], v[170:171], v[162:163]
	v_pk_fma_f32 v[42:43], v[42:43], v[172:173], v[164:165]
	global_store_dwordx4 v155, v[44:47], s[76:77] nt
	global_store_dwordx4 v155, v[40:43], s[76:77] offset:16 nt
	v_mul_f32_e32 v32, v32, v157
	v_mul_f32_e32 v33, v33, v157
	v_mul_f32_e32 v34, v34, v157
	v_mul_f32_e32 v35, v35, v157
	v_mul_f32_e32 v36, v36, v157
	v_mul_f32_e32 v37, v37, v157
	v_mul_f32_e32 v38, v38, v157
	v_mul_f32_e32 v39, v39, v157
	v_exp_f32_e32 v32, v32
	v_exp_f32_e32 v33, v33
	v_exp_f32_e32 v34, v34
	v_exp_f32_e32 v35, v35
	v_exp_f32_e32 v36, v36
	v_exp_f32_e32 v37, v37
	v_exp_f32_e32 v38, v38
	v_exp_f32_e32 v39, v39
	v_add_f32_e32 v32, 1.0, v32
	v_add_f32_e32 v33, 1.0, v33
	v_add_f32_e32 v34, 1.0, v34
	v_add_f32_e32 v35, 1.0, v35
	v_add_f32_e32 v36, 1.0, v36
	v_add_f32_e32 v37, 1.0, v37
	v_add_f32_e32 v38, 1.0, v38
	v_add_f32_e32 v39, 1.0, v39
	v_rcp_f32_e32 v32, v32
	v_rcp_f32_e32 v33, v33
	v_rcp_f32_e32 v34, v34
	v_rcp_f32_e32 v35, v35
	v_rcp_f32_e32 v36, v36
	v_rcp_f32_e32 v37, v37
	v_rcp_f32_e32 v38, v38
	v_rcp_f32_e32 v39, v39
	v_lshlrev_b32_e32 v158, 16, v204
	v_and_b32_e32 v159, 0xffff0000, v204
	v_lshlrev_b32_e32 v166, 16, v212
	v_and_b32_e32 v167, 0xffff0000, v212
	v_lshlrev_b32_e32 v160, 16, v205
	v_and_b32_e32 v161, 0xffff0000, v205
	v_lshlrev_b32_e32 v168, 16, v213
	v_and_b32_e32 v169, 0xffff0000, v213
	v_lshlrev_b32_e32 v162, 16, v206
	v_and_b32_e32 v163, 0xffff0000, v206
	v_lshlrev_b32_e32 v170, 16, v214
	v_and_b32_e32 v171, 0xffff0000, v214
	v_lshlrev_b32_e32 v164, 16, v207
	v_and_b32_e32 v165, 0xffff0000, v207
	v_lshlrev_b32_e32 v172, 16, v215
	v_and_b32_e32 v173, 0xffff0000, v215
	v_pk_fma_f32 v[36:37], v[36:37], v[166:167], v[158:159]
	v_pk_fma_f32 v[38:39], v[38:39], v[168:169], v[160:161]
	v_pk_fma_f32 v[32:33], v[32:33], v[170:171], v[162:163]
	v_pk_fma_f32 v[34:35], v[34:35], v[172:173], v[164:165]
	global_store_dwordx4 v155, v[36:39], s[76:77] offset:512 nt
	global_store_dwordx4 v155, v[32:35], s[76:77] offset:528 nt
	s_waitcnt vmcnt(17)
	v_fmamk_f32 v157, v234, 0x3a800000, v154
	v_rsq_f32_e32 v157, v157
	s_add_u32 s76, s80, 0xa0000
	s_addc_u32 s77, s81, 0
	v_mul_f32_e32 v157, 0xbfb8aa3b, v157
	v_mul_f32_e32 v24, v24, v157
	v_mul_f32_e32 v25, v25, v157
	v_mul_f32_e32 v26, v26, v157
	v_mul_f32_e32 v27, v27, v157
	v_mul_f32_e32 v28, v28, v157
	v_mul_f32_e32 v29, v29, v157
	v_mul_f32_e32 v30, v30, v157
	v_mul_f32_e32 v31, v31, v157
	v_exp_f32_e32 v24, v24
	v_exp_f32_e32 v25, v25
	v_exp_f32_e32 v26, v26
	v_exp_f32_e32 v27, v27
	v_exp_f32_e32 v28, v28
	v_exp_f32_e32 v29, v29
	v_exp_f32_e32 v30, v30
	v_exp_f32_e32 v31, v31
	v_add_f32_e32 v24, 1.0, v24
	v_add_f32_e32 v25, 1.0, v25
	v_add_f32_e32 v26, 1.0, v26
	v_add_f32_e32 v27, 1.0, v27
	v_add_f32_e32 v28, 1.0, v28
	v_add_f32_e32 v29, 1.0, v29
	v_add_f32_e32 v30, 1.0, v30
	v_add_f32_e32 v31, 1.0, v31
	v_rcp_f32_e32 v24, v24
	v_rcp_f32_e32 v25, v25
	v_rcp_f32_e32 v26, v26
	v_rcp_f32_e32 v27, v27
	v_rcp_f32_e32 v28, v28
	v_rcp_f32_e32 v29, v29
	v_rcp_f32_e32 v30, v30
	v_rcp_f32_e32 v31, v31
	v_lshlrev_b32_e32 v158, 16, v218
	v_and_b32_e32 v159, 0xffff0000, v218
	v_lshlrev_b32_e32 v166, 16, v226
	v_and_b32_e32 v167, 0xffff0000, v226
	v_lshlrev_b32_e32 v160, 16, v219
	v_and_b32_e32 v161, 0xffff0000, v219
	v_lshlrev_b32_e32 v168, 16, v227
	v_and_b32_e32 v169, 0xffff0000, v227
	v_lshlrev_b32_e32 v162, 16, v220
	v_and_b32_e32 v163, 0xffff0000, v220
	v_lshlrev_b32_e32 v170, 16, v228
	v_and_b32_e32 v171, 0xffff0000, v228
	v_lshlrev_b32_e32 v164, 16, v221
	v_and_b32_e32 v165, 0xffff0000, v221
	v_lshlrev_b32_e32 v172, 16, v229
	v_and_b32_e32 v173, 0xffff0000, v229
	v_pk_fma_f32 v[28:29], v[28:29], v[166:167], v[158:159]
	v_pk_fma_f32 v[30:31], v[30:31], v[168:169], v[160:161]
	v_pk_fma_f32 v[24:25], v[24:25], v[170:171], v[162:163]
	v_pk_fma_f32 v[26:27], v[26:27], v[172:173], v[164:165]
	global_store_dwordx4 v155, v[28:31], s[76:77] nt
;     __device__ __forceinline__ void operator()(const f32x4 (&acc)[2][2][4][2], const Unit& u, int wr, int wc, int fr, int fq) const {
;     ...
;             for (int m = 0; m < 4; ++m) { const int row = row0 + ai * HALF + m * 16; const size_t off = (size_t)row * ldc + col0;
;                 const float nrl = -1.4426950408889634f * __builtin_amdgcn_rsqf(__hip_atomic_load(rowsq + row, __ATOMIC_RELAXED, __HIP_MEMORY_SCOPE_AGENT) * (1.f / (float)ldc) + eps);
; #pragma unroll
;                 for (int bj = 0; bj < 2; ++bj) { const size_t o2 = off + bj * HALF; const u32x4 xw = *(const u32x4*)(xb + o2), g = *(const u32x4*)(pl + o2);
;                     f32x4 b0, b1, p0, p1;
;                     b0[0] = __uint_as_float(xw.x << 16); b0[1] = __uint_as_float(xw.x & 0xffff0000u); b0[2] = __uint_as_float(xw.y << 16); b0[3] = __uint_as_float(xw.y & 0xffff0000u);
;                     b1[0] = __uint_as_float(xw.z << 16); b1[1] = __uint_as_float(xw.z & 0xffff0000u); b1[2] = __uint_as_float(xw.w << 16); b1[3] = __uint_as_float(xw.w & 0xffff0000u);
;                     p0[0] = __uint_as_float(g.x << 16); p0[1] = __uint_as_float(g.x & 0xffff0000u); p0[2] = __uint_as_float(g.y << 16); p0[3] = __uint_as_float(g.y & 0xffff0000u);
;                     p1[0] = __uint_as_float(g.z << 16); p1[1] = __uint_as_float(g.z & 0xffff0000u); p1[2] = __uint_as_float(g.w << 16); p1[3] = __uint_as_float(g.w & 0xffff0000u);
;                     f32x4 s0, s1;
; #pragma unroll
;                     for (int e = 0; e < 4; ++e) { s0[e] = __builtin_amdgcn_rcpf(1.f + __builtin_amdgcn_exp2f(nrl * acc[ai][bj][m][0][e])); s1[e] = __builtin_amdgcn_rcpf(1.f + __builtin_amdgcn_exp2f(nrl * acc[ai][bj][m][1][e])); }
;                     *(f32x4*)(out + o2) = b0 + s0 * p0; *(f32x4*)(out + o2 + 4) = b1 + s1 * p1; }
;                 if (m & 1) asm volatile("" ::: "memory"); }
	global_store_dwordx4 v155, v[24:27], s[76:77] offset:16 nt
	v_mul_f32_e32 v16, v16, v157
	v_mul_f32_e32 v17, v17, v157
	v_mul_f32_e32 v18, v18, v157
	v_mul_f32_e32 v19, v19, v157
	v_mul_f32_e32 v20, v20, v157
	v_mul_f32_e32 v21, v21, v157
	v_mul_f32_e32 v22, v22, v157
	v_mul_f32_e32 v23, v23, v157
	v_exp_f32_e32 v16, v16
	v_exp_f32_e32 v17, v17
	v_exp_f32_e32 v18, v18
	v_exp_f32_e32 v19, v19
	v_exp_f32_e32 v20, v20
	v_exp_f32_e32 v21, v21
	v_exp_f32_e32 v22, v22
	v_exp_f32_e32 v23, v23
	v_add_f32_e32 v16, 1.0, v16
	v_add_f32_e32 v17, 1.0, v17
	v_add_f32_e32 v18, 1.0, v18
	v_add_f32_e32 v19, 1.0, v19
	v_add_f32_e32 v20, 1.0, v20
	v_add_f32_e32 v21, 1.0, v21
	v_add_f32_e32 v22, 1.0, v22
	v_add_f32_e32 v23, 1.0, v23
	v_rcp_f32_e32 v16, v16
	v_rcp_f32_e32 v17, v17
	v_rcp_f32_e32 v18, v18
	v_rcp_f32_e32 v19, v19
	v_rcp_f32_e32 v20, v20
	v_rcp_f32_e32 v21, v21
	v_rcp_f32_e32 v22, v22
	v_rcp_f32_e32 v23, v23
	v_lshlrev_b32_e32 v158, 16, v222
	v_and_b32_e32 v159, 0xffff0000, v222
	v_lshlrev_b32_e32 v166, 16, v230
	v_and_b32_e32 v167, 0xffff0000, v230
	v_lshlrev_b32_e32 v160, 16, v223
	v_and_b32_e32 v161, 0xffff0000, v223
	v_lshlrev_b32_e32 v168, 16, v231
	v_and_b32_e32 v169, 0xffff0000, v231
	v_lshlrev_b32_e32 v162, 16, v224
	v_and_b32_e32 v163, 0xffff0000, v224
	v_lshlrev_b32_e32 v170, 16, v232
	v_and_b32_e32 v171, 0xffff0000, v232
	v_lshlrev_b32_e32 v164, 16, v225
	v_and_b32_e32 v165, 0xffff0000, v225
	v_lshlrev_b32_e32 v172, 16, v233
	v_and_b32_e32 v173, 0xffff0000, v233
	v_pk_fma_f32 v[20:21], v[20:21], v[166:167], v[158:159]
	v_pk_fma_f32 v[22:23], v[22:23], v[168:169], v[160:161]
	v_pk_fma_f32 v[16:17], v[16:17], v[170:171], v[162:163]
	v_pk_fma_f32 v[18:19], v[18:19], v[172:173], v[164:165]
	global_store_dwordx4 v155, v[20:23], s[76:77] offset:512 nt
	global_store_dwordx4 v155, v[16:19], s[76:77] offset:528 nt
	s_waitcnt vmcnt(12)
	v_fmamk_f32 v157, v252, 0x3a800000, v154
	v_rsq_f32_e32 v157, v157
	s_add_u32 s76, s80, 0xb0000
	s_addc_u32 s77, s81, 0
	v_mul_f32_e32 v157, 0xbfb8aa3b, v157
	v_mul_f32_e32 v8, v8, v157
	v_mul_f32_e32 v9, v9, v157
	v_mul_f32_e32 v10, v10, v157
	v_mul_f32_e32 v11, v11, v157
	v_mul_f32_e32 v12, v12, v157
	v_mul_f32_e32 v13, v13, v157
	v_mul_f32_e32 v14, v14, v157
	v_mul_f32_e32 v15, v15, v157
	v_exp_f32_e32 v8, v8
	v_exp_f32_e32 v9, v9
	v_exp_f32_e32 v10, v10
	v_exp_f32_e32 v11, v11
	v_exp_f32_e32 v12, v12
	v_exp_f32_e32 v13, v13
	v_exp_f32_e32 v14, v14
	v_exp_f32_e32 v15, v15
	v_add_f32_e32 v8, 1.0, v8
	v_add_f32_e32 v9, 1.0, v9
	v_add_f32_e32 v10, 1.0, v10
	v_add_f32_e32 v11, 1.0, v11
	v_add_f32_e32 v12, 1.0, v12
	v_add_f32_e32 v13, 1.0, v13
	v_add_f32_e32 v14, 1.0, v14
	v_add_f32_e32 v15, 1.0, v15
	v_rcp_f32_e32 v8, v8
	v_rcp_f32_e32 v9, v9
	v_rcp_f32_e32 v10, v10
	v_rcp_f32_e32 v11, v11
	v_rcp_f32_e32 v12, v12
	v_rcp_f32_e32 v13, v13
	v_rcp_f32_e32 v14, v14
	v_rcp_f32_e32 v15, v15
	v_lshlrev_b32_e32 v158, 16, v236
	v_and_b32_e32 v159, 0xffff0000, v236
	v_lshlrev_b32_e32 v166, 16, v244
	v_and_b32_e32 v167, 0xffff0000, v244
	v_lshlrev_b32_e32 v160, 16, v237
	v_and_b32_e32 v161, 0xffff0000, v237
	v_lshlrev_b32_e32 v168, 16, v245
	v_and_b32_e32 v169, 0xffff0000, v245
	v_lshlrev_b32_e32 v162, 16, v238
	v_and_b32_e32 v163, 0xffff0000, v238
	v_lshlrev_b32_e32 v170, 16, v246
	v_and_b32_e32 v171, 0xffff0000, v246
	v_lshlrev_b32_e32 v164, 16, v239
	v_and_b32_e32 v165, 0xffff0000, v239
	v_lshlrev_b32_e32 v172, 16, v247
	v_and_b32_e32 v173, 0xffff0000, v247
	v_pk_fma_f32 v[12:13], v[12:13], v[166:167], v[158:159]
	v_pk_fma_f32 v[14:15], v[14:15], v[168:169], v[160:161]
	v_pk_fma_f32 v[8:9], v[8:9], v[170:171], v[162:163]
	v_pk_fma_f32 v[10:11], v[10:11], v[172:173], v[164:165]
	global_store_dwordx4 v155, v[12:15], s[76:77] nt
	global_store_dwordx4 v155, v[8:11], s[76:77] offset:16 nt
	v_mul_f32_e32 v0, v0, v157
	v_mul_f32_e32 v1, v1, v157
	v_mul_f32_e32 v2, v2, v157
	v_mul_f32_e32 v3, v3, v157
	v_mul_f32_e32 v4, v4, v157
	v_mul_f32_e32 v5, v5, v157
	v_mul_f32_e32 v6, v6, v157
	v_mul_f32_e32 v7, v7, v157
	v_exp_f32_e32 v0, v0
	v_exp_f32_e32 v1, v1
	v_exp_f32_e32 v2, v2
	v_exp_f32_e32 v3, v3
	v_exp_f32_e32 v4, v4
	v_exp_f32_e32 v5, v5
	v_exp_f32_e32 v6, v6
	v_exp_f32_e32 v7, v7
	v_add_f32_e32 v0, 1.0, v0
	v_add_f32_e32 v1, 1.0, v1
	v_add_f32_e32 v2, 1.0, v2
	v_add_f32_e32 v3, 1.0, v3
	v_add_f32_e32 v4, 1.0, v4
	v_add_f32_e32 v5, 1.0, v5
	v_add_f32_e32 v6, 1.0, v6
	v_add_f32_e32 v7, 1.0, v7
	v_rcp_f32_e32 v0, v0
	v_rcp_f32_e32 v1, v1
	v_rcp_f32_e32 v2, v2
	v_rcp_f32_e32 v3, v3
	v_rcp_f32_e32 v4, v4
	v_rcp_f32_e32 v5, v5
	v_rcp_f32_e32 v6, v6
	v_rcp_f32_e32 v7, v7
	v_lshlrev_b32_e32 v158, 16, v240
	v_and_b32_e32 v159, 0xffff0000, v240
	v_lshlrev_b32_e32 v166, 16, v248
	v_and_b32_e32 v167, 0xffff0000, v248
	v_lshlrev_b32_e32 v160, 16, v241
	v_and_b32_e32 v161, 0xffff0000, v241
	v_lshlrev_b32_e32 v168, 16, v249
	v_and_b32_e32 v169, 0xffff0000, v249
	v_lshlrev_b32_e32 v162, 16, v242
	v_and_b32_e32 v163, 0xffff0000, v242
	v_lshlrev_b32_e32 v170, 16, v250
	v_and_b32_e32 v171, 0xffff0000, v250
	v_lshlrev_b32_e32 v164, 16, v243
	v_and_b32_e32 v165, 0xffff0000, v243
	v_lshlrev_b32_e32 v172, 16, v251
	v_and_b32_e32 v173, 0xffff0000, v251
	v_pk_fma_f32 v[4:5], v[4:5], v[166:167], v[158:159]
	v_pk_fma_f32 v[6:7], v[6:7], v[168:169], v[160:161]
	v_pk_fma_f32 v[0:1], v[0:1], v[170:171], v[162:163]
	v_pk_fma_f32 v[2:3], v[2:3], v[172:173], v[164:165]
	global_store_dwordx4 v155, v[4:7], s[76:77] offset:512 nt
	global_store_dwordx4 v155, v[0:3], s[76:77] offset:528 nt
	s_cbranch_vccnz .LBB0_716
	s_andn2_b64 vcc, exec, s[4:5]
	s_cbranch_vccnz .LBB0_715
	s_barrier
	s_branch .LBB0_715
